# all GEMM phases switched from aligned epilogues to base mode (leading half epilogue overlaps trailing half last MFMA block, no extra per-unit barriers); stacks on v15
# baseline (speedup 1.0000x reference)
; #define PG8_STAGE(bufoff, gbase, voff) do { _Pragma("unroll") for (int _i = 0; _i < 2; ++_i) \
;         __builtin_amdgcn_global_load_lds((const unsigned*)((const char*)(gbase) + (voff)[_i]), (PG8_LAS unsigned*)(lds + (bufoff) + ldsw + _i * 8192), 16, 0, 0); } while (0)
; #define PG8_LDA(dst, b, h) do { _Pragma("unroll") for (int m = 0; m < 4; ++m) _Pragma("unroll") for (int k = 0; k < 2; ++k) dst[m][k] = *(const PG8_LAS bf16x8*)(lds + PG8_SA(b, h) + aoff + m * 2048 + k * 1024); } while (0)
; #define PG8_LDB(dst, b, h) do { _Pragma("unroll") for (int n = 0; n < 2; ++n) _Pragma("unroll") for (int k = 0; k < 2; ++k) dst[n][k] = *(const PG8_LAS bf16x8*)(lds + PG8_SB(b, h) + boff + n * 2048 + k * 1024); } while (0)
; #define PG8_MMA(ai, bj, At, Bt) do { __builtin_amdgcn_s_setprio(1); _Pragma("unroll") for (int m = 0; m < 4; ++m) _Pragma("unroll") for (int n = 0; n < 2; ++n) _Pragma("unroll") for (int k = 0; k < 2; ++k) \
;         acc[ai][bj][m][n] = __builtin_amdgcn_mfma_f32_16x16x32_bf16(Bt[n][k], At[m][k], acc[ai][bj][m][n], 0, 0, 0); __builtin_amdgcn_s_setprio(0); } while (0)
; #define PG8_WAIT_V(n) asm volatile("s_waitcnt vmcnt(" #n ")" ::: "memory")
; #define PG8_WAIT_L(n) asm volatile("s_waitcnt lgkmcnt(" #n ")" ::: "memory")
; #define PG8_BAR __builtin_amdgcn_s_barrier()
; #define PG8_SCHED __builtin_amdgcn_sched_barrier(0)
; template <class Epi, class Sched, bool ALIGN_EPI = false, bool SP2 = false>
; __device__ __forceinline__ void gemm_phase(PG8_LAS unsigned char* lds, const Gemm g, const Sched& S, const Epi& E) {
;     ...
;             PG8_LDB(B0, 0, 0); PG8_LDB(B1, 0, 1); PG8_SCHED; PG8_LDA(At, 0, 0); PG8_STAGE(PG8_SA(1, 1), a1 + hstep, voffA);
;             PG8_WAIT_V(8); PG8_WAIT_L(0); PG8_BAR; PG8_MMA(0, 0, At, B0); PG8_MMA(0, 1, At, B1); PG8_BAR; PG8_SCHED;
;             PG8_LDA(At, 0, 1); PG8_STAGE(PG8_SB(0, 0), b2, voffB); PG8_STAGE(PG8_SB(0, 1), b2 + hstep, voffB); PG8_STAGE(PG8_SA(0, 0), a2, voffA);
.LBB0_205:
	ds_read_b128 v[128:131], v190
	ds_read_b128 v[132:135], v190 offset:1024
	ds_read_b128 v[136:139], v190 offset:2048
	ds_read_b128 v[140:143], v190 offset:3072
	ds_read_b128 v[144:147], v191
	ds_read_b128 v[148:151], v191 offset:1024
	ds_read_b128 v[152:155], v191 offset:2048
	ds_read_b128 v[156:159], v191 offset:3072
	s_add_u32 s6, s4, 0xfff80080
	s_addc_u32 s7, s5, -1
	s_cmp_eq_u32 s51, 28
	s_cselect_b32 s29, s1, s7
	s_cselect_b32 s28, s3, s6
	s_cselect_b32 s7, s21, s50
	s_cselect_b32 s6, s23, s33
	v_lshl_add_u64 v[184:185], s[4:5], 0, v[172:173]
	s_add_i32 m0, s31, 0xc000
	ds_read_b128 v[180:183], v192
	ds_read_b128 v[194:197], v192 offset:1024
	ds_read_b128 v[198:201], v192 offset:2048
	ds_read_b128 v[202:205], v192 offset:3072
	ds_read_b128 v[206:209], v192 offset:4096
	ds_read_b128 v[210:213], v192 offset:5120
	ds_read_b128 v[214:217], v192 offset:6144
	ds_read_b128 v[218:221], v192 offset:7168
	global_load_lds_dwordx4 v[184:185], off
	v_lshl_add_u64 v[184:185], s[4:5], 0, v[174:175]
	s_add_i32 m0, s31, 0xe000
	s_nop 0
	global_load_lds_dwordx4 v[184:185], off
	s_waitcnt vmcnt(8)
	s_waitcnt lgkmcnt(0)
	s_barrier
	s_setprio 1
	s_waitcnt lgkmcnt(0)
	v_mfma_f32_16x16x32_bf16 v[124:127], v[128:131], v[180:183], v[124:127]
	v_mfma_f32_16x16x32_bf16 v[120:123], v[136:139], v[180:183], v[120:123]
	v_mfma_f32_16x16x32_bf16 v[108:111], v[128:131], v[198:201], v[108:111]
	v_mfma_f32_16x16x32_bf16 v[104:107], v[136:139], v[198:201], v[104:107]
	v_mfma_f32_16x16x32_bf16 v[92:95], v[128:131], v[206:209], v[92:95]
	v_mfma_f32_16x16x32_bf16 v[88:91], v[136:139], v[206:209], v[88:91]
	v_mfma_f32_16x16x32_bf16 v[76:79], v[128:131], v[214:217], v[76:79]
	v_mfma_f32_16x16x32_bf16 v[72:75], v[136:139], v[214:217], v[72:75]
	v_mfma_f32_16x16x32_bf16 v[124:127], v[132:135], v[194:197], v[124:127]
	v_mfma_f32_16x16x32_bf16 v[120:123], v[140:143], v[194:197], v[120:123]
	v_mfma_f32_16x16x32_bf16 v[108:111], v[132:135], v[202:205], v[108:111]
	v_mfma_f32_16x16x32_bf16 v[104:107], v[140:143], v[202:205], v[104:107]
	v_mfma_f32_16x16x32_bf16 v[92:95], v[132:135], v[210:213], v[92:95]
	v_mfma_f32_16x16x32_bf16 v[88:91], v[140:143], v[210:213], v[88:91]
	v_mfma_f32_16x16x32_bf16 v[76:79], v[132:135], v[218:221], v[76:79]
	v_mfma_f32_16x16x32_bf16 v[72:75], v[140:143], v[218:221], v[72:75]
	s_setprio 0
	s_setprio 1
	v_mfma_f32_16x16x32_bf16 v[116:119], v[144:147], v[180:183], v[116:119]
	v_mfma_f32_16x16x32_bf16 v[112:115], v[152:155], v[180:183], v[112:115]
	v_mfma_f32_16x16x32_bf16 v[100:103], v[144:147], v[198:201], v[100:103]
	v_mfma_f32_16x16x32_bf16 v[96:99], v[152:155], v[198:201], v[96:99]
	v_mfma_f32_16x16x32_bf16 v[84:87], v[144:147], v[206:209], v[84:87]
	v_mfma_f32_16x16x32_bf16 v[80:83], v[152:155], v[206:209], v[80:83]
	v_mfma_f32_16x16x32_bf16 v[68:71], v[144:147], v[214:217], v[68:71]
	v_mfma_f32_16x16x32_bf16 v[64:67], v[152:155], v[214:217], v[64:67]
	v_mfma_f32_16x16x32_bf16 v[116:119], v[148:151], v[194:197], v[116:119]
	v_mfma_f32_16x16x32_bf16 v[112:115], v[156:159], v[194:197], v[112:115]
	v_mfma_f32_16x16x32_bf16 v[100:103], v[148:151], v[202:205], v[100:103]
	v_mfma_f32_16x16x32_bf16 v[96:99], v[156:159], v[202:205], v[96:99]
	v_mfma_f32_16x16x32_bf16 v[84:87], v[148:151], v[210:213], v[84:87]
	v_mfma_f32_16x16x32_bf16 v[80:83], v[156:159], v[210:213], v[80:83]
	v_mfma_f32_16x16x32_bf16 v[68:71], v[148:151], v[218:221], v[68:71]
	v_mfma_f32_16x16x32_bf16 v[64:67], v[156:159], v[218:221], v[64:67]
	s_setprio 0
	s_barrier
	s_add_i32 s52, s43, s30
	v_lshl_add_u64 v[184:185], s[6:7], 0, v[164:165]
	s_mov_b32 m0, s52
	ds_read_b128 v[180:183], v192 offset:16384
	ds_read_b128 v[194:197], v192 offset:17408
	ds_read_b128 v[198:201], v192 offset:18432
	ds_read_b128 v[202:205], v192 offset:19456
	ds_read_b128 v[206:209], v192 offset:20480
	ds_read_b128 v[210:213], v192 offset:21504
	ds_read_b128 v[214:217], v192 offset:22528
	ds_read_b128 v[218:221], v192 offset:23552
	global_load_lds_dwordx4 v[184:185], off
	s_add_i32 m0, s52, 0x2000
	s_add_u32 s52, s6, 0x80000
	v_lshl_add_u64 v[222:223], s[6:7], 0, v[168:169]
	s_addc_u32 s53, s7, 0
	s_add_i32 s54, s44, s30
	global_load_lds_dwordx4 v[222:223], off
	v_lshl_add_u64 v[224:225], s[52:53], 0, v[164:165]
	s_mov_b32 m0, s54
	v_lshl_add_u64 v[226:227], s[28:29], 0, v[166:167]
	global_load_lds_dwordx4 v[224:225], off
	v_lshl_add_u64 v[224:225], s[52:53], 0, v[168:169]
	s_add_i32 m0, s54, 0x2000
	s_nop 0
	global_load_lds_dwordx4 v[224:225], off
	v_lshl_add_u64 v[224:225], s[28:29], 0, v[162:163]
	s_mov_b32 m0, s31
	s_nop 0
	global_load_lds_dwordx4 v[224:225], off
	s_mov_b32 m0, s34
	s_nop 0
	global_load_lds_dwordx4 v[226:227], off
	s_waitcnt vmcnt(8)
	s_waitcnt lgkmcnt(0)
	s_barrier
; #define PG8_STAGE(bufoff, gbase, voff) do { _Pragma("unroll") for (int _i = 0; _i < 2; ++_i) \
;         __builtin_amdgcn_global_load_lds((const unsigned*)((const char*)(gbase) + (voff)[_i]), (PG8_LAS unsigned*)(lds + (bufoff) + ldsw + _i * 8192), 16, 0, 0); } while (0)
; #define PG8_LDA(dst, b, h) do { _Pragma("unroll") for (int m = 0; m < 4; ++m) _Pragma("unroll") for (int k = 0; k < 2; ++k) dst[m][k] = *(const PG8_LAS bf16x8*)(lds + PG8_SA(b, h) + aoff + m * 2048 + k * 1024); } while (0)
; #define PG8_LDB(dst, b, h) do { _Pragma("unroll") for (int n = 0; n < 2; ++n) _Pragma("unroll") for (int k = 0; k < 2; ++k) dst[n][k] = *(const PG8_LAS bf16x8*)(lds + PG8_SB(b, h) + boff + n * 2048 + k * 1024); } while (0)
; #define PG8_MMA(ai, bj, At, Bt) do { __builtin_amdgcn_s_setprio(1); _Pragma("unroll") for (int m = 0; m < 4; ++m) _Pragma("unroll") for (int n = 0; n < 2; ++n) _Pragma("unroll") for (int k = 0; k < 2; ++k) \
;         acc[ai][bj][m][n] = __builtin_amdgcn_mfma_f32_16x16x32_bf16(Bt[n][k], At[m][k], acc[ai][bj][m][n], 0, 0, 0); __builtin_amdgcn_s_setprio(0); } while (0)
; #define PG8_WAIT_V(n) asm volatile("s_waitcnt vmcnt(" #n ")" ::: "memory")
; #define PG8_WAIT_L(n) asm volatile("s_waitcnt lgkmcnt(" #n ")" ::: "memory")
; #define PG8_BAR __builtin_amdgcn_s_barrier()
; #define PG8_SCHED __builtin_amdgcn_sched_barrier(0)
; template <class Epi, class Sched, bool ALIGN_EPI = false, bool SP2 = false>
; __device__ __forceinline__ void gemm_phase(PG8_LAS unsigned char* lds, const Gemm g, const Sched& S, const Epi& E) {
;     ...
;             PG8_WAIT_V(8); PG8_WAIT_L(0); PG8_BAR; PG8_MMA(1, 0, At, B0); PG8_MMA(1, 1, At, B1); PG8_BAR; PG8_SCHED;
;             PG8_LDB(B0, 1, 0); PG8_LDB(B1, 1, 1); PG8_SCHED; PG8_LDA(At, 1, 0); PG8_STAGE(PG8_SA(0, 1), a2 + hstep, voffA);
;             PG8_WAIT_V(8); PG8_WAIT_L(0); PG8_BAR; PG8_MMA(0, 0, At, B0); PG8_MMA(0, 1, At, B1); PG8_BAR; PG8_SCHED;
	s_setprio 1
	s_waitcnt lgkmcnt(0)
	v_mfma_f32_16x16x32_bf16 v[60:63], v[128:131], v[180:183], v[60:63]
	v_mfma_f32_16x16x32_bf16 v[56:59], v[136:139], v[180:183], v[56:59]
	v_mfma_f32_16x16x32_bf16 v[44:47], v[128:131], v[198:201], v[44:47]
	v_mfma_f32_16x16x32_bf16 v[40:43], v[136:139], v[198:201], v[40:43]
	v_mfma_f32_16x16x32_bf16 v[28:31], v[128:131], v[206:209], v[28:31]
	v_mfma_f32_16x16x32_bf16 v[24:27], v[136:139], v[206:209], v[24:27]
	v_mfma_f32_16x16x32_bf16 v[12:15], v[128:131], v[214:217], v[12:15]
	v_mfma_f32_16x16x32_bf16 v[8:11], v[136:139], v[214:217], v[8:11]
	v_mfma_f32_16x16x32_bf16 v[60:63], v[132:135], v[194:197], v[60:63]
	v_mfma_f32_16x16x32_bf16 v[56:59], v[140:143], v[194:197], v[56:59]
	v_mfma_f32_16x16x32_bf16 v[44:47], v[132:135], v[202:205], v[44:47]
	v_mfma_f32_16x16x32_bf16 v[40:43], v[140:143], v[202:205], v[40:43]
	v_mfma_f32_16x16x32_bf16 v[28:31], v[132:135], v[210:213], v[28:31]
	v_mfma_f32_16x16x32_bf16 v[24:27], v[140:143], v[210:213], v[24:27]
	v_mfma_f32_16x16x32_bf16 v[12:15], v[132:135], v[218:221], v[12:15]
	v_mfma_f32_16x16x32_bf16 v[8:11], v[140:143], v[218:221], v[8:11]
	s_setprio 0
	s_setprio 1
	v_mfma_f32_16x16x32_bf16 v[52:55], v[144:147], v[180:183], v[52:55]
	v_mfma_f32_16x16x32_bf16 v[48:51], v[152:155], v[180:183], v[48:51]
	v_mfma_f32_16x16x32_bf16 v[36:39], v[144:147], v[198:201], v[36:39]
	v_mfma_f32_16x16x32_bf16 v[32:35], v[152:155], v[198:201], v[32:35]
	v_mfma_f32_16x16x32_bf16 v[20:23], v[144:147], v[206:209], v[20:23]
	v_mfma_f32_16x16x32_bf16 v[16:19], v[152:155], v[206:209], v[16:19]
	v_mfma_f32_16x16x32_bf16 v[4:7], v[144:147], v[214:217], v[4:7]
	v_mfma_f32_16x16x32_bf16 v[0:3], v[152:155], v[214:217], v[0:3]
	v_mfma_f32_16x16x32_bf16 v[52:55], v[148:151], v[194:197], v[52:55]
	v_mfma_f32_16x16x32_bf16 v[48:51], v[156:159], v[194:197], v[48:51]
	v_mfma_f32_16x16x32_bf16 v[36:39], v[148:151], v[202:205], v[36:39]
	v_mfma_f32_16x16x32_bf16 v[32:35], v[156:159], v[202:205], v[32:35]
	v_mfma_f32_16x16x32_bf16 v[20:23], v[148:151], v[210:213], v[20:23]
	v_mfma_f32_16x16x32_bf16 v[16:19], v[156:159], v[210:213], v[16:19]
	v_mfma_f32_16x16x32_bf16 v[4:7], v[148:151], v[218:221], v[4:7]
	v_mfma_f32_16x16x32_bf16 v[0:3], v[156:159], v[218:221], v[0:3]
	s_setprio 0
	s_barrier
	s_add_i32 s52, 0, 0x18000
	s_add_i32 s53, 0, 0x1c000
	v_add_u32_e32 v140, s52, v188
	v_add_u32_e32 v156, s53, v188
	ds_read_b128 v[128:131], v140
	ds_read_b128 v[132:135], v140 offset:1024
	ds_read_b128 v[136:139], v140 offset:2048
	ds_read_b128 v[140:143], v140 offset:3072
	ds_read_b128 v[144:147], v156
	ds_read_b128 v[148:151], v156 offset:1024
	ds_read_b128 v[152:155], v156 offset:2048
	ds_read_b128 v[156:159], v156 offset:3072
	s_add_u32 s28, s28, 0x80000
	s_addc_u32 s29, s29, 0
	s_mov_b32 m0, s35
	v_lshl_add_u64 v[228:229], s[28:29], 0, v[162:163]
	ds_read_b128 v[180:183], v192 offset:32768
	ds_read_b128 v[194:197], v192 offset:33792
	ds_read_b128 v[198:201], v192 offset:34816
	ds_read_b128 v[202:205], v192 offset:35840
	ds_read_b128 v[206:209], v192 offset:36864
	ds_read_b128 v[210:213], v192 offset:37888
	ds_read_b128 v[214:217], v192 offset:38912
	ds_read_b128 v[218:221], v192 offset:39936
	global_load_lds_dwordx4 v[228:229], off
	v_lshl_add_u64 v[228:229], s[28:29], 0, v[166:167]
	s_mov_b32 m0, s36
	s_nop 0
	global_load_lds_dwordx4 v[228:229], off
	s_waitcnt vmcnt(8)
	s_waitcnt lgkmcnt(0)
	s_barrier
	s_setprio 1
	s_waitcnt lgkmcnt(0)
	v_mfma_f32_16x16x32_bf16 v[124:127], v[128:131], v[180:183], v[124:127]
	v_mfma_f32_16x16x32_bf16 v[120:123], v[136:139], v[180:183], v[120:123]
	v_mfma_f32_16x16x32_bf16 v[108:111], v[128:131], v[198:201], v[108:111]
	v_mfma_f32_16x16x32_bf16 v[104:107], v[136:139], v[198:201], v[104:107]
	v_mfma_f32_16x16x32_bf16 v[92:95], v[128:131], v[206:209], v[92:95]
	v_mfma_f32_16x16x32_bf16 v[88:91], v[136:139], v[206:209], v[88:91]
	v_mfma_f32_16x16x32_bf16 v[76:79], v[128:131], v[214:217], v[76:79]
	v_mfma_f32_16x16x32_bf16 v[72:75], v[136:139], v[214:217], v[72:75]
	v_mfma_f32_16x16x32_bf16 v[124:127], v[132:135], v[194:197], v[124:127]
	v_mfma_f32_16x16x32_bf16 v[120:123], v[140:143], v[194:197], v[120:123]
	v_mfma_f32_16x16x32_bf16 v[108:111], v[132:135], v[202:205], v[108:111]
	v_mfma_f32_16x16x32_bf16 v[104:107], v[140:143], v[202:205], v[104:107]
	v_mfma_f32_16x16x32_bf16 v[92:95], v[132:135], v[210:213], v[92:95]
	v_mfma_f32_16x16x32_bf16 v[88:91], v[140:143], v[210:213], v[88:91]
	v_mfma_f32_16x16x32_bf16 v[76:79], v[132:135], v[218:221], v[76:79]
	v_mfma_f32_16x16x32_bf16 v[72:75], v[140:143], v[218:221], v[72:75]
	s_setprio 0
	s_setprio 1
	v_mfma_f32_16x16x32_bf16 v[116:119], v[144:147], v[180:183], v[116:119]
	v_mfma_f32_16x16x32_bf16 v[112:115], v[152:155], v[180:183], v[112:115]
	v_mfma_f32_16x16x32_bf16 v[100:103], v[144:147], v[198:201], v[100:103]
	v_mfma_f32_16x16x32_bf16 v[96:99], v[152:155], v[198:201], v[96:99]
	v_mfma_f32_16x16x32_bf16 v[84:87], v[144:147], v[206:209], v[84:87]
	v_mfma_f32_16x16x32_bf16 v[80:83], v[152:155], v[206:209], v[80:83]
	v_mfma_f32_16x16x32_bf16 v[68:71], v[144:147], v[214:217], v[68:71]
	v_mfma_f32_16x16x32_bf16 v[64:67], v[152:155], v[214:217], v[64:67]
	v_mfma_f32_16x16x32_bf16 v[116:119], v[148:151], v[194:197], v[116:119]
	v_mfma_f32_16x16x32_bf16 v[112:115], v[156:159], v[194:197], v[112:115]
	v_mfma_f32_16x16x32_bf16 v[100:103], v[148:151], v[202:205], v[100:103]
	v_mfma_f32_16x16x32_bf16 v[96:99], v[156:159], v[202:205], v[96:99]
	v_mfma_f32_16x16x32_bf16 v[84:87], v[148:151], v[210:213], v[84:87]
	v_mfma_f32_16x16x32_bf16 v[80:83], v[156:159], v[210:213], v[80:83]
	v_mfma_f32_16x16x32_bf16 v[68:71], v[148:151], v[218:221], v[68:71]
	v_mfma_f32_16x16x32_bf16 v[64:67], v[156:159], v[218:221], v[64:67]
	s_setprio 0
	s_barrier
; #define PG8_STAGE(bufoff, gbase, voff) do { _Pragma("unroll") for (int _i = 0; _i < 2; ++_i) \
;         __builtin_amdgcn_global_load_lds((const unsigned*)((const char*)(gbase) + (voff)[_i]), (PG8_LAS unsigned*)(lds + (bufoff) + ldsw + _i * 8192), 16, 0, 0); } while (0)
; #define PG8_LDA(dst, b, h) do { _Pragma("unroll") for (int m = 0; m < 4; ++m) _Pragma("unroll") for (int k = 0; k < 2; ++k) dst[m][k] = *(const PG8_LAS bf16x8*)(lds + PG8_SA(b, h) + aoff + m * 2048 + k * 1024); } while (0)
; #define PG8_MMA(ai, bj, At, Bt) do { __builtin_amdgcn_s_setprio(1); _Pragma("unroll") for (int m = 0; m < 4; ++m) _Pragma("unroll") for (int n = 0; n < 2; ++n) _Pragma("unroll") for (int k = 0; k < 2; ++k) \
;         acc[ai][bj][m][n] = __builtin_amdgcn_mfma_f32_16x16x32_bf16(Bt[n][k], At[m][k], acc[ai][bj][m][n], 0, 0, 0); __builtin_amdgcn_s_setprio(0); } while (0)
; #define PG8_WAIT_V(n) asm volatile("s_waitcnt vmcnt(" #n ")" ::: "memory")
; #define PG8_WAIT_L(n) asm volatile("s_waitcnt lgkmcnt(" #n ")" ::: "memory")
; #define PG8_BAR __builtin_amdgcn_s_barrier()
; #define PG8_SCHED __builtin_amdgcn_sched_barrier(0)
; template <class Epi, class Sched, bool ALIGN_EPI = false, bool SP2 = false>
; __device__ __forceinline__ void gemm_phase(PG8_LAS unsigned char* lds, const Gemm g, const Sched& S, const Epi& E) {
;     ...
;             PG8_LDA(At, 1, 1); PG8_STAGE(PG8_SB(1, 0), b3, voffB); PG8_STAGE(PG8_SB(1, 1), b3 + hstep, voffB); PG8_STAGE(PG8_SA(1, 0), a3, voffA);
;             PG8_WAIT_V(8); PG8_WAIT_L(0); PG8_BAR; PG8_MMA(1, 0, At, B0); PG8_MMA(1, 1, At, B1); PG8_BAR; PG8_SCHED;
;     ...
;         if constexpr (ALIGN_EPI) { if (wr == 0) PG8_BAR; }
;         if constexpr (!Epi::AFTER_DRAIN) { E(acc, cur, wr, wc, fr, fq); S.done(cur); }
	s_add_i32 s28, s52, s30
	v_lshl_add_u64 v[184:185], v[184:185], 0, s[16:17]
	s_mov_b32 m0, s28
	ds_read_b128 v[180:183], v192 offset:49152
	ds_read_b128 v[194:197], v192 offset:50176
	ds_read_b128 v[198:201], v192 offset:51200
	ds_read_b128 v[202:205], v192 offset:52224
	ds_read_b128 v[206:209], v192 offset:53248
	ds_read_b128 v[210:213], v192 offset:54272
	ds_read_b128 v[214:217], v192 offset:55296
	ds_read_b128 v[218:221], v192 offset:56320
	global_load_lds_dwordx4 v[184:185], off
	s_add_i32 m0, s28, 0x2000
	s_add_u32 s6, s6, 0x80080
	v_lshl_add_u64 v[184:185], v[222:223], 0, s[16:17]
	s_addc_u32 s7, s7, 0
	s_add_i32 s28, s53, s30
	global_load_lds_dwordx4 v[184:185], off
	v_lshl_add_u64 v[184:185], s[6:7], 0, v[164:165]
	s_mov_b32 m0, s28
	s_nop 0
	global_load_lds_dwordx4 v[184:185], off
	v_lshl_add_u64 v[184:185], s[6:7], 0, v[168:169]
	s_add_i32 m0, s28, 0x2000
	s_nop 0
	global_load_lds_dwordx4 v[184:185], off
	v_lshl_add_u64 v[184:185], v[224:225], 0, s[16:17]
	s_mov_b32 m0, s38
	s_nop 0
	global_load_lds_dwordx4 v[184:185], off
	v_lshl_add_u64 v[184:185], v[226:227], 0, s[16:17]
	s_mov_b32 m0, s39
	s_nop 0
	global_load_lds_dwordx4 v[184:185], off
	s_waitcnt vmcnt(8)
	s_waitcnt lgkmcnt(0)
	s_barrier
	s_setprio 1
	s_waitcnt lgkmcnt(0)
	v_mfma_f32_16x16x32_bf16 v[60:63], v[128:131], v[180:183], v[60:63]
	v_mfma_f32_16x16x32_bf16 v[56:59], v[136:139], v[180:183], v[56:59]
	v_mfma_f32_16x16x32_bf16 v[44:47], v[128:131], v[198:201], v[44:47]
	v_mfma_f32_16x16x32_bf16 v[40:43], v[136:139], v[198:201], v[40:43]
	v_mfma_f32_16x16x32_bf16 v[28:31], v[128:131], v[206:209], v[28:31]
	v_mfma_f32_16x16x32_bf16 v[24:27], v[136:139], v[206:209], v[24:27]
	v_mfma_f32_16x16x32_bf16 v[12:15], v[128:131], v[214:217], v[12:15]
	v_mfma_f32_16x16x32_bf16 v[8:11], v[136:139], v[214:217], v[8:11]
	v_mfma_f32_16x16x32_bf16 v[60:63], v[132:135], v[194:197], v[60:63]
	v_mfma_f32_16x16x32_bf16 v[56:59], v[140:143], v[194:197], v[56:59]
	v_mfma_f32_16x16x32_bf16 v[44:47], v[132:135], v[202:205], v[44:47]
	v_mfma_f32_16x16x32_bf16 v[40:43], v[140:143], v[202:205], v[40:43]
	v_mfma_f32_16x16x32_bf16 v[28:31], v[132:135], v[210:213], v[28:31]
	v_mfma_f32_16x16x32_bf16 v[24:27], v[140:143], v[210:213], v[24:27]
	v_mfma_f32_16x16x32_bf16 v[12:15], v[132:135], v[218:221], v[12:15]
	v_mfma_f32_16x16x32_bf16 v[8:11], v[140:143], v[218:221], v[8:11]
	s_setprio 0
	s_setprio 1
	v_mfma_f32_16x16x32_bf16 v[52:55], v[144:147], v[180:183], v[52:55]
	v_mfma_f32_16x16x32_bf16 v[48:51], v[152:155], v[180:183], v[48:51]
	v_mfma_f32_16x16x32_bf16 v[36:39], v[144:147], v[198:201], v[36:39]
	v_mfma_f32_16x16x32_bf16 v[32:35], v[152:155], v[198:201], v[32:35]
	v_mfma_f32_16x16x32_bf16 v[20:23], v[144:147], v[206:209], v[20:23]
	v_mfma_f32_16x16x32_bf16 v[16:19], v[152:155], v[206:209], v[16:19]
	v_mfma_f32_16x16x32_bf16 v[4:7], v[144:147], v[214:217], v[4:7]
	v_mfma_f32_16x16x32_bf16 v[0:3], v[152:155], v[214:217], v[0:3]
	v_mfma_f32_16x16x32_bf16 v[52:55], v[148:151], v[194:197], v[52:55]
	v_mfma_f32_16x16x32_bf16 v[48:51], v[156:159], v[194:197], v[48:51]
	v_mfma_f32_16x16x32_bf16 v[36:39], v[148:151], v[202:205], v[36:39]
	v_mfma_f32_16x16x32_bf16 v[32:35], v[156:159], v[202:205], v[32:35]
	v_mfma_f32_16x16x32_bf16 v[20:23], v[148:151], v[210:213], v[20:23]
	v_mfma_f32_16x16x32_bf16 v[16:19], v[156:159], v[210:213], v[16:19]
	v_mfma_f32_16x16x32_bf16 v[4:7], v[148:151], v[218:221], v[4:7]
	v_mfma_f32_16x16x32_bf16 v[0:3], v[156:159], v[218:221], v[0:3]
	s_setprio 0
	s_barrier
	s_add_i32 s51, s51, 2
	s_add_u32 s4, s4, 0x100
	s_addc_u32 s5, s5, 0
	s_add_u32 s33, s33, 0x100
	s_addc_u32 s50, s50, 0
	s_cmp_gt_u32 s51, 29
	s_cbranch_scc0 .LBB0_205
	s_and_b64 vcc, exec, s[18:19]
	s_cbranch_vccz .LBB0_208
.LBB0_208:
	s_and_b32 s1, s0, -4
	v_lshl_add_u32 v182, s2, 8, v161
	v_lshl_or_b32 v170, s0, 8, v189
	s_cmp_lg_u32 s1, 4
	s_mov_b64 s[2:3], -1
	s_cbranch_scc1 .LBB0_211
	s_and_b64 vcc, exec, s[2:3]
	s_cbranch_vccnz .LBB0_260

; #define PG8_WAIT_V(n) asm volatile("s_waitcnt vmcnt(" #n ")" ::: "memory")
; #define PG8_BAR __builtin_amdgcn_s_barrier()
; template <class Epi, class Sched, bool ALIGN_EPI = false, bool SP2 = false>
; __device__ __forceinline__ void gemm_phase(PG8_LAS unsigned char* lds, const Gemm g, const Sched& S, const Epi& E) {
;     ...
;         cur = nxt; cA = nA; cB = nB; ++ui;
;         if constexpr (ALIGN_EPI) { if (wr == 1) PG8_BAR; }
;     }
;     PG8_WAIT_V(0);
;     if constexpr (!ALIGN_EPI) { if (wr == 0) PG8_BAR; }
;     PG8_BAR;
.LBB0_261:
	s_andn2_b64 vcc, exec, s[12:13]
	s_cbranch_vccnz .LBB0_197
	s_branch .LBB0_197
.LBB0_263:
	s_waitcnt vmcnt(0)
	s_and_b64 vcc, exec, s[18:19]
	s_cbranch_vccz .Lnoalign_p2
	s_barrier
.Lnoalign_p2:
	s_barrier

; #define PG8_STAGE(bufoff, gbase, voff) do { _Pragma("unroll") for (int _i = 0; _i < 2; ++_i) \
;         __builtin_amdgcn_global_load_lds((const unsigned*)((const char*)(gbase) + (voff)[_i]), (PG8_LAS unsigned*)(lds + (bufoff) + ldsw + _i * 8192), 16, 0, 0); } while (0)
; #define PG8_LDA(dst, b, h) do { _Pragma("unroll") for (int m = 0; m < 4; ++m) _Pragma("unroll") for (int k = 0; k < 2; ++k) dst[m][k] = *(const PG8_LAS bf16x8*)(lds + PG8_SA(b, h) + aoff + m * 2048 + k * 1024); } while (0)
; #define PG8_LDB(dst, b, h) do { _Pragma("unroll") for (int n = 0; n < 2; ++n) _Pragma("unroll") for (int k = 0; k < 2; ++k) dst[n][k] = *(const PG8_LAS bf16x8*)(lds + PG8_SB(b, h) + boff + n * 2048 + k * 1024); } while (0)
; #define PG8_MMA(ai, bj, At, Bt) do { __builtin_amdgcn_s_setprio(1); _Pragma("unroll") for (int m = 0; m < 4; ++m) _Pragma("unroll") for (int n = 0; n < 2; ++n) _Pragma("unroll") for (int k = 0; k < 2; ++k) \
;         acc[ai][bj][m][n] = __builtin_amdgcn_mfma_f32_16x16x32_bf16(Bt[n][k], At[m][k], acc[ai][bj][m][n], 0, 0, 0); __builtin_amdgcn_s_setprio(0); } while (0)
; #define PG8_WAIT_V(n) asm volatile("s_waitcnt vmcnt(" #n ")" ::: "memory")
; #define PG8_WAIT_L(n) asm volatile("s_waitcnt lgkmcnt(" #n ")" ::: "memory")
; #define PG8_BAR __builtin_amdgcn_s_barrier()
; #define PG8_SCHED __builtin_amdgcn_sched_barrier(0)
; template <class Epi, class Sched, bool ALIGN_EPI = false, bool SP2 = false>
; __device__ __forceinline__ void gemm_phase(PG8_LAS unsigned char* lds, const Gemm g, const Sched& S, const Epi& E) {
;     ...
;             PG8_LDB(B0, 0, 0); PG8_LDB(B1, 0, 1); PG8_SCHED; PG8_LDA(At, 0, 0); PG8_STAGE(PG8_SA(1, 1), a1 + hstep, voffA);
;             PG8_WAIT_V(8); PG8_WAIT_L(0); PG8_BAR; PG8_MMA(0, 0, At, B0); PG8_MMA(0, 1, At, B1); PG8_BAR; PG8_SCHED;
;             PG8_LDA(At, 0, 1); PG8_STAGE(PG8_SB(0, 0), b2, voffB); PG8_STAGE(PG8_SB(0, 1), b2 + hstep, voffB); PG8_STAGE(PG8_SA(0, 0), a2, voffA);
.LBB0_572:
	ds_read_b128 v[146:149], v159
	ds_read_b128 v[150:153], v159 offset:1024
	ds_read_b128 v[164:167], v159 offset:2048
	ds_read_b128 v[168:171], v159 offset:3072
	ds_read_b128 v[172:175], v161
	ds_read_b128 v[176:179], v161 offset:1024
	ds_read_b128 v[180:183], v161 offset:2048
	ds_read_b128 v[188:191], v161 offset:3072
	s_add_u32 s24, s22, 0xfffc0080
	s_addc_u32 s25, s23, -1
	s_cmp_eq_u32 s46, 12
	s_cselect_b32 s27, s7, s25
	s_cselect_b32 s26, s15, s24
	s_cselect_b32 s25, s13, s45
	s_cselect_b32 s24, s21, s44
	v_lshl_add_u64 v[154:155], s[22:23], 0, v[138:139]
	s_add_i32 m0, s31, 0xc000
	ds_read_b128 v[192:195], v162
	ds_read_b128 v[196:199], v162 offset:1024
	ds_read_b128 v[200:203], v162 offset:2048
	ds_read_b128 v[204:207], v162 offset:3072
	ds_read_b128 v[208:211], v162 offset:4096
	ds_read_b128 v[212:215], v162 offset:5120
	ds_read_b128 v[216:219], v162 offset:6144
	ds_read_b128 v[220:223], v162 offset:7168
	global_load_lds_dwordx4 v[154:155], off
	v_lshl_add_u64 v[154:155], s[22:23], 0, v[140:141]
	s_add_i32 m0, s31, 0xe000
	s_nop 0
	global_load_lds_dwordx4 v[154:155], off
	s_waitcnt vmcnt(8)
	s_waitcnt lgkmcnt(0)
	s_barrier
	s_setprio 1
	s_waitcnt lgkmcnt(0)
	v_mfma_f32_16x16x32_bf16 v[124:127], v[146:149], v[192:195], v[124:127]
	v_mfma_f32_16x16x32_bf16 v[120:123], v[164:167], v[192:195], v[120:123]
	v_mfma_f32_16x16x32_bf16 v[108:111], v[146:149], v[200:203], v[108:111]
	v_mfma_f32_16x16x32_bf16 v[104:107], v[164:167], v[200:203], v[104:107]
	v_mfma_f32_16x16x32_bf16 v[92:95], v[146:149], v[208:211], v[92:95]
	v_mfma_f32_16x16x32_bf16 v[88:91], v[164:167], v[208:211], v[88:91]
	v_mfma_f32_16x16x32_bf16 v[76:79], v[146:149], v[216:219], v[76:79]
	v_mfma_f32_16x16x32_bf16 v[72:75], v[164:167], v[216:219], v[72:75]
	v_mfma_f32_16x16x32_bf16 v[124:127], v[150:153], v[196:199], v[124:127]
	v_mfma_f32_16x16x32_bf16 v[120:123], v[168:171], v[196:199], v[120:123]
	v_mfma_f32_16x16x32_bf16 v[108:111], v[150:153], v[204:207], v[108:111]
	v_mfma_f32_16x16x32_bf16 v[104:107], v[168:171], v[204:207], v[104:107]
	v_mfma_f32_16x16x32_bf16 v[92:95], v[150:153], v[212:215], v[92:95]
	v_mfma_f32_16x16x32_bf16 v[88:91], v[168:171], v[212:215], v[88:91]
	v_mfma_f32_16x16x32_bf16 v[76:79], v[150:153], v[220:223], v[76:79]
	v_mfma_f32_16x16x32_bf16 v[72:75], v[168:171], v[220:223], v[72:75]
	s_setprio 0
	s_setprio 1
	v_mfma_f32_16x16x32_bf16 v[116:119], v[172:175], v[192:195], v[116:119]
	v_mfma_f32_16x16x32_bf16 v[112:115], v[180:183], v[192:195], v[112:115]
	v_mfma_f32_16x16x32_bf16 v[100:103], v[172:175], v[200:203], v[100:103]
	v_mfma_f32_16x16x32_bf16 v[96:99], v[180:183], v[200:203], v[96:99]
	v_mfma_f32_16x16x32_bf16 v[84:87], v[172:175], v[208:211], v[84:87]
	v_mfma_f32_16x16x32_bf16 v[80:83], v[180:183], v[208:211], v[80:83]
	v_mfma_f32_16x16x32_bf16 v[68:71], v[172:175], v[216:219], v[68:71]
	v_mfma_f32_16x16x32_bf16 v[64:67], v[180:183], v[216:219], v[64:67]
	v_mfma_f32_16x16x32_bf16 v[116:119], v[176:179], v[196:199], v[116:119]
	v_mfma_f32_16x16x32_bf16 v[112:115], v[188:191], v[196:199], v[112:115]
	v_mfma_f32_16x16x32_bf16 v[100:103], v[176:179], v[204:207], v[100:103]
	v_mfma_f32_16x16x32_bf16 v[96:99], v[188:191], v[204:207], v[96:99]
	v_mfma_f32_16x16x32_bf16 v[84:87], v[176:179], v[212:215], v[84:87]
	v_mfma_f32_16x16x32_bf16 v[80:83], v[188:191], v[212:215], v[80:83]
	v_mfma_f32_16x16x32_bf16 v[68:71], v[176:179], v[220:223], v[68:71]
	v_mfma_f32_16x16x32_bf16 v[64:67], v[188:191], v[220:223], v[64:67]
	s_setprio 0
	s_barrier
	s_add_i32 s47, s39, s28
	v_lshl_add_u64 v[154:155], s[24:25], 0, v[130:131]
	s_mov_b32 m0, s47
	ds_read_b128 v[192:195], v162 offset:16384
	ds_read_b128 v[196:199], v162 offset:17408
	ds_read_b128 v[200:203], v162 offset:18432
	ds_read_b128 v[204:207], v162 offset:19456
	ds_read_b128 v[208:211], v162 offset:20480
	ds_read_b128 v[212:215], v162 offset:21504
	ds_read_b128 v[216:219], v162 offset:22528
	ds_read_b128 v[220:223], v162 offset:23552
	global_load_lds_dwordx4 v[154:155], off
	s_add_i32 m0, s47, 0x2000
	s_add_u32 s48, s24, 0x40000
	v_lshl_add_u64 v[184:185], s[24:25], 0, v[134:135]
	s_addc_u32 s49, s25, 0
	s_add_i32 s47, s40, s28
	global_load_lds_dwordx4 v[184:185], off
	v_lshl_add_u64 v[224:225], s[48:49], 0, v[130:131]
	s_mov_b32 m0, s47
	v_lshl_add_u64 v[226:227], s[26:27], 0, v[132:133]
	global_load_lds_dwordx4 v[224:225], off
	v_lshl_add_u64 v[224:225], s[48:49], 0, v[134:135]
	s_add_i32 m0, s47, 0x2000
	s_nop 0
	global_load_lds_dwordx4 v[224:225], off
	v_lshl_add_u64 v[224:225], s[26:27], 0, v[128:129]
	s_mov_b32 m0, s31
	s_nop 0
	global_load_lds_dwordx4 v[224:225], off
	s_mov_b32 m0, s33
	s_nop 0
	global_load_lds_dwordx4 v[226:227], off
	s_waitcnt vmcnt(8)
	s_waitcnt lgkmcnt(0)
	s_barrier
; #define PG8_STAGE(bufoff, gbase, voff) do { _Pragma("unroll") for (int _i = 0; _i < 2; ++_i) \
;         __builtin_amdgcn_global_load_lds((const unsigned*)((const char*)(gbase) + (voff)[_i]), (PG8_LAS unsigned*)(lds + (bufoff) + ldsw + _i * 8192), 16, 0, 0); } while (0)
; #define PG8_LDA(dst, b, h) do { _Pragma("unroll") for (int m = 0; m < 4; ++m) _Pragma("unroll") for (int k = 0; k < 2; ++k) dst[m][k] = *(const PG8_LAS bf16x8*)(lds + PG8_SA(b, h) + aoff + m * 2048 + k * 1024); } while (0)
; #define PG8_LDB(dst, b, h) do { _Pragma("unroll") for (int n = 0; n < 2; ++n) _Pragma("unroll") for (int k = 0; k < 2; ++k) dst[n][k] = *(const PG8_LAS bf16x8*)(lds + PG8_SB(b, h) + boff + n * 2048 + k * 1024); } while (0)
; #define PG8_MMA(ai, bj, At, Bt) do { __builtin_amdgcn_s_setprio(1); _Pragma("unroll") for (int m = 0; m < 4; ++m) _Pragma("unroll") for (int n = 0; n < 2; ++n) _Pragma("unroll") for (int k = 0; k < 2; ++k) \
;         acc[ai][bj][m][n] = __builtin_amdgcn_mfma_f32_16x16x32_bf16(Bt[n][k], At[m][k], acc[ai][bj][m][n], 0, 0, 0); __builtin_amdgcn_s_setprio(0); } while (0)
; #define PG8_WAIT_V(n) asm volatile("s_waitcnt vmcnt(" #n ")" ::: "memory")
; #define PG8_WAIT_L(n) asm volatile("s_waitcnt lgkmcnt(" #n ")" ::: "memory")
; #define PG8_BAR __builtin_amdgcn_s_barrier()
; #define PG8_SCHED __builtin_amdgcn_sched_barrier(0)
; template <class Epi, class Sched, bool ALIGN_EPI = false, bool SP2 = false>
; __device__ __forceinline__ void gemm_phase(PG8_LAS unsigned char* lds, const Gemm g, const Sched& S, const Epi& E) {
;     ...
;             PG8_WAIT_V(8); PG8_WAIT_L(0); PG8_BAR; PG8_MMA(1, 0, At, B0); PG8_MMA(1, 1, At, B1); PG8_BAR; PG8_SCHED;
;             PG8_LDB(B0, 1, 0); PG8_LDB(B1, 1, 1); PG8_SCHED; PG8_LDA(At, 1, 0); PG8_STAGE(PG8_SA(0, 1), a2 + hstep, voffA);
;             PG8_WAIT_V(8); PG8_WAIT_L(0); PG8_BAR; PG8_MMA(0, 0, At, B0); PG8_MMA(0, 1, At, B1); PG8_BAR; PG8_SCHED;
	s_setprio 1
	s_waitcnt lgkmcnt(0)
	v_mfma_f32_16x16x32_bf16 v[60:63], v[146:149], v[192:195], v[60:63]
	v_mfma_f32_16x16x32_bf16 v[56:59], v[164:167], v[192:195], v[56:59]
	v_mfma_f32_16x16x32_bf16 v[44:47], v[146:149], v[200:203], v[44:47]
	v_mfma_f32_16x16x32_bf16 v[40:43], v[164:167], v[200:203], v[40:43]
	v_mfma_f32_16x16x32_bf16 v[28:31], v[146:149], v[208:211], v[28:31]
	v_mfma_f32_16x16x32_bf16 v[24:27], v[164:167], v[208:211], v[24:27]
	v_mfma_f32_16x16x32_bf16 v[12:15], v[146:149], v[216:219], v[12:15]
	v_mfma_f32_16x16x32_bf16 v[8:11], v[164:167], v[216:219], v[8:11]
	v_mfma_f32_16x16x32_bf16 v[60:63], v[150:153], v[196:199], v[60:63]
	v_mfma_f32_16x16x32_bf16 v[56:59], v[168:171], v[196:199], v[56:59]
	v_mfma_f32_16x16x32_bf16 v[44:47], v[150:153], v[204:207], v[44:47]
	v_mfma_f32_16x16x32_bf16 v[40:43], v[168:171], v[204:207], v[40:43]
	v_mfma_f32_16x16x32_bf16 v[28:31], v[150:153], v[212:215], v[28:31]
	v_mfma_f32_16x16x32_bf16 v[24:27], v[168:171], v[212:215], v[24:27]
	v_mfma_f32_16x16x32_bf16 v[12:15], v[150:153], v[220:223], v[12:15]
	v_mfma_f32_16x16x32_bf16 v[8:11], v[168:171], v[220:223], v[8:11]
	s_setprio 0
	s_setprio 1
	v_mfma_f32_16x16x32_bf16 v[52:55], v[172:175], v[192:195], v[52:55]
	v_mfma_f32_16x16x32_bf16 v[48:51], v[180:183], v[192:195], v[48:51]
	v_mfma_f32_16x16x32_bf16 v[36:39], v[172:175], v[200:203], v[36:39]
	v_mfma_f32_16x16x32_bf16 v[32:35], v[180:183], v[200:203], v[32:35]
	v_mfma_f32_16x16x32_bf16 v[20:23], v[172:175], v[208:211], v[20:23]
	v_mfma_f32_16x16x32_bf16 v[16:19], v[180:183], v[208:211], v[16:19]
	v_mfma_f32_16x16x32_bf16 v[4:7], v[172:175], v[216:219], v[4:7]
	v_mfma_f32_16x16x32_bf16 v[0:3], v[180:183], v[216:219], v[0:3]
	v_mfma_f32_16x16x32_bf16 v[52:55], v[176:179], v[196:199], v[52:55]
	v_mfma_f32_16x16x32_bf16 v[48:51], v[188:191], v[196:199], v[48:51]
	v_mfma_f32_16x16x32_bf16 v[36:39], v[176:179], v[204:207], v[36:39]
	v_mfma_f32_16x16x32_bf16 v[32:35], v[188:191], v[204:207], v[32:35]
	v_mfma_f32_16x16x32_bf16 v[20:23], v[176:179], v[212:215], v[20:23]
	v_mfma_f32_16x16x32_bf16 v[16:19], v[188:191], v[212:215], v[16:19]
	v_mfma_f32_16x16x32_bf16 v[4:7], v[176:179], v[220:223], v[4:7]
	v_mfma_f32_16x16x32_bf16 v[0:3], v[188:191], v[220:223], v[0:3]
	s_setprio 0
	s_barrier
	s_add_i32 s47, 0, 0x18000
	v_add_u32_e32 v136, s47, v157
	s_add_i32 s48, 0, 0x1c000
	ds_read_b128 v[146:149], v136
	ds_read_b128 v[150:153], v136 offset:1024
	ds_read_b128 v[164:167], v136 offset:2048
	ds_read_b128 v[168:171], v136 offset:3072
	v_add_u32_e32 v136, s48, v157
	ds_read_b128 v[172:175], v136
	ds_read_b128 v[176:179], v136 offset:1024
	ds_read_b128 v[180:183], v136 offset:2048
	ds_read_b128 v[188:191], v136 offset:3072
	s_add_u32 s26, s26, 0x40000
	s_addc_u32 s27, s27, 0
	s_mov_b32 m0, s34
	v_lshl_add_u64 v[228:229], s[26:27], 0, v[128:129]
	ds_read_b128 v[192:195], v162 offset:32768
	ds_read_b128 v[196:199], v162 offset:33792
	ds_read_b128 v[200:203], v162 offset:34816
	ds_read_b128 v[204:207], v162 offset:35840
	ds_read_b128 v[208:211], v162 offset:36864
	ds_read_b128 v[212:215], v162 offset:37888
	ds_read_b128 v[216:219], v162 offset:38912
	ds_read_b128 v[220:223], v162 offset:39936
	global_load_lds_dwordx4 v[228:229], off
	v_lshl_add_u64 v[228:229], s[26:27], 0, v[132:133]
	s_mov_b32 m0, s35
	s_nop 0
	global_load_lds_dwordx4 v[228:229], off
	s_waitcnt vmcnt(8)
	s_waitcnt lgkmcnt(0)
	s_barrier
	s_setprio 1
	s_waitcnt lgkmcnt(0)
	v_mfma_f32_16x16x32_bf16 v[124:127], v[146:149], v[192:195], v[124:127]
	v_mfma_f32_16x16x32_bf16 v[120:123], v[164:167], v[192:195], v[120:123]
	v_mfma_f32_16x16x32_bf16 v[108:111], v[146:149], v[200:203], v[108:111]
	v_mfma_f32_16x16x32_bf16 v[104:107], v[164:167], v[200:203], v[104:107]
	v_mfma_f32_16x16x32_bf16 v[92:95], v[146:149], v[208:211], v[92:95]
	v_mfma_f32_16x16x32_bf16 v[88:91], v[164:167], v[208:211], v[88:91]
	v_mfma_f32_16x16x32_bf16 v[76:79], v[146:149], v[216:219], v[76:79]
	v_mfma_f32_16x16x32_bf16 v[72:75], v[164:167], v[216:219], v[72:75]
	v_mfma_f32_16x16x32_bf16 v[124:127], v[150:153], v[196:199], v[124:127]
	v_mfma_f32_16x16x32_bf16 v[120:123], v[168:171], v[196:199], v[120:123]
	v_mfma_f32_16x16x32_bf16 v[108:111], v[150:153], v[204:207], v[108:111]
	v_mfma_f32_16x16x32_bf16 v[104:107], v[168:171], v[204:207], v[104:107]
	v_mfma_f32_16x16x32_bf16 v[92:95], v[150:153], v[212:215], v[92:95]
	v_mfma_f32_16x16x32_bf16 v[88:91], v[168:171], v[212:215], v[88:91]
	v_mfma_f32_16x16x32_bf16 v[76:79], v[150:153], v[220:223], v[76:79]
	v_mfma_f32_16x16x32_bf16 v[72:75], v[168:171], v[220:223], v[72:75]
	s_setprio 0
	s_setprio 1
	v_mfma_f32_16x16x32_bf16 v[116:119], v[172:175], v[192:195], v[116:119]
	v_mfma_f32_16x16x32_bf16 v[112:115], v[180:183], v[192:195], v[112:115]
	v_mfma_f32_16x16x32_bf16 v[100:103], v[172:175], v[200:203], v[100:103]
	v_mfma_f32_16x16x32_bf16 v[96:99], v[180:183], v[200:203], v[96:99]
	v_mfma_f32_16x16x32_bf16 v[84:87], v[172:175], v[208:211], v[84:87]
	v_mfma_f32_16x16x32_bf16 v[80:83], v[180:183], v[208:211], v[80:83]
	v_mfma_f32_16x16x32_bf16 v[68:71], v[172:175], v[216:219], v[68:71]
	v_mfma_f32_16x16x32_bf16 v[64:67], v[180:183], v[216:219], v[64:67]
	v_mfma_f32_16x16x32_bf16 v[116:119], v[176:179], v[196:199], v[116:119]
	v_mfma_f32_16x16x32_bf16 v[112:115], v[188:191], v[196:199], v[112:115]
	v_mfma_f32_16x16x32_bf16 v[100:103], v[176:179], v[204:207], v[100:103]
	v_mfma_f32_16x16x32_bf16 v[96:99], v[188:191], v[204:207], v[96:99]
	v_mfma_f32_16x16x32_bf16 v[84:87], v[176:179], v[212:215], v[84:87]
	v_mfma_f32_16x16x32_bf16 v[80:83], v[188:191], v[212:215], v[80:83]
	v_mfma_f32_16x16x32_bf16 v[68:71], v[176:179], v[220:223], v[68:71]
	v_mfma_f32_16x16x32_bf16 v[64:67], v[188:191], v[220:223], v[64:67]
	s_setprio 0
	s_barrier
; #define PG8_STAGE(bufoff, gbase, voff) do { _Pragma("unroll") for (int _i = 0; _i < 2; ++_i) \
;         __builtin_amdgcn_global_load_lds((const unsigned*)((const char*)(gbase) + (voff)[_i]), (PG8_LAS unsigned*)(lds + (bufoff) + ldsw + _i * 8192), 16, 0, 0); } while (0)
; #define PG8_LDA(dst, b, h) do { _Pragma("unroll") for (int m = 0; m < 4; ++m) _Pragma("unroll") for (int k = 0; k < 2; ++k) dst[m][k] = *(const PG8_LAS bf16x8*)(lds + PG8_SA(b, h) + aoff + m * 2048 + k * 1024); } while (0)
; #define PG8_MMA(ai, bj, At, Bt) do { __builtin_amdgcn_s_setprio(1); _Pragma("unroll") for (int m = 0; m < 4; ++m) _Pragma("unroll") for (int n = 0; n < 2; ++n) _Pragma("unroll") for (int k = 0; k < 2; ++k) \
;         acc[ai][bj][m][n] = __builtin_amdgcn_mfma_f32_16x16x32_bf16(Bt[n][k], At[m][k], acc[ai][bj][m][n], 0, 0, 0); __builtin_amdgcn_s_setprio(0); } while (0)
; #define PG8_WAIT_V(n) asm volatile("s_waitcnt vmcnt(" #n ")" ::: "memory")
; #define PG8_WAIT_L(n) asm volatile("s_waitcnt lgkmcnt(" #n ")" ::: "memory")
; #define PG8_BAR __builtin_amdgcn_s_barrier()
; #define PG8_SCHED __builtin_amdgcn_sched_barrier(0)
;     __device__ __forceinline__ void operator()(const f32x4 (&acc)[2][2][4][2], const Unit& u, int wr, int wc, int fr, int fq) const {
;         const int br = u.pm >= 64 ? 1 : 0, pm = u.pm & 63, pn = u.pn & 7;
;         const int row0 = pm * BM + wr * 64 + fr, col0 = pn * BM + wc * 32 + 8 * fq, gcol = (br ? 4608 : 6656) + col0;
; template <class Epi, class Sched, bool ALIGN_EPI = false, bool SP2 = false>
; __device__ __forceinline__ void gemm_phase(PG8_LAS unsigned char* lds, const Gemm g, const Sched& S, const Epi& E) {
;     ...
;             PG8_LDA(At, 1, 1); PG8_STAGE(PG8_SB(1, 0), b3, voffB); PG8_STAGE(PG8_SB(1, 1), b3 + hstep, voffB); PG8_STAGE(PG8_SA(1, 0), a3, voffA);
;             PG8_WAIT_V(8); PG8_WAIT_L(0); PG8_BAR; PG8_MMA(1, 0, At, B0); PG8_MMA(1, 1, At, B1); PG8_BAR; PG8_SCHED;
	s_add_i32 s26, s47, s28
	v_lshl_add_u64 v[154:155], v[154:155], 0, s[8:9]
	s_mov_b32 m0, s26
	ds_read_b128 v[192:195], v162 offset:49152
	ds_read_b128 v[196:199], v162 offset:50176
	ds_read_b128 v[200:203], v162 offset:51200
	ds_read_b128 v[204:207], v162 offset:52224
	ds_read_b128 v[208:211], v162 offset:53248
	ds_read_b128 v[212:215], v162 offset:54272
	ds_read_b128 v[216:219], v162 offset:55296
	ds_read_b128 v[220:223], v162 offset:56320
	global_load_lds_dwordx4 v[154:155], off
	s_add_i32 m0, s26, 0x2000
	s_add_u32 s24, s24, 0x40080
	v_lshl_add_u64 v[154:155], v[184:185], 0, s[8:9]
	s_addc_u32 s25, s25, 0
	s_add_i32 s26, s48, s28
	global_load_lds_dwordx4 v[154:155], off
	v_lshl_add_u64 v[154:155], s[24:25], 0, v[130:131]
	s_mov_b32 m0, s26
	s_nop 0
	global_load_lds_dwordx4 v[154:155], off
	v_lshl_add_u64 v[154:155], s[24:25], 0, v[134:135]
	s_add_i32 m0, s26, 0x2000
	s_nop 0
	global_load_lds_dwordx4 v[154:155], off
	v_lshl_add_u64 v[154:155], v[224:225], 0, s[8:9]
	s_mov_b32 m0, s36
	s_nop 0
	global_load_lds_dwordx4 v[154:155], off
	v_lshl_add_u64 v[154:155], v[226:227], 0, s[8:9]
	s_mov_b32 m0, s37
	s_nop 0
	global_load_lds_dwordx4 v[154:155], off
	s_waitcnt vmcnt(8)
	s_waitcnt lgkmcnt(0)
	s_barrier
	s_setprio 1
	s_waitcnt lgkmcnt(0)
	v_mfma_f32_16x16x32_bf16 v[60:63], v[146:149], v[192:195], v[60:63]
	v_mfma_f32_16x16x32_bf16 v[56:59], v[164:167], v[192:195], v[56:59]
	v_mfma_f32_16x16x32_bf16 v[44:47], v[146:149], v[200:203], v[44:47]
	v_mfma_f32_16x16x32_bf16 v[40:43], v[164:167], v[200:203], v[40:43]
	v_mfma_f32_16x16x32_bf16 v[28:31], v[146:149], v[208:211], v[28:31]
	v_mfma_f32_16x16x32_bf16 v[24:27], v[164:167], v[208:211], v[24:27]
	v_mfma_f32_16x16x32_bf16 v[12:15], v[146:149], v[216:219], v[12:15]
	v_mfma_f32_16x16x32_bf16 v[8:11], v[164:167], v[216:219], v[8:11]
	v_mfma_f32_16x16x32_bf16 v[60:63], v[150:153], v[196:199], v[60:63]
	v_mfma_f32_16x16x32_bf16 v[56:59], v[168:171], v[196:199], v[56:59]
	v_mfma_f32_16x16x32_bf16 v[44:47], v[150:153], v[204:207], v[44:47]
	v_mfma_f32_16x16x32_bf16 v[40:43], v[168:171], v[204:207], v[40:43]
	v_mfma_f32_16x16x32_bf16 v[28:31], v[150:153], v[212:215], v[28:31]
	v_mfma_f32_16x16x32_bf16 v[24:27], v[168:171], v[212:215], v[24:27]
	v_mfma_f32_16x16x32_bf16 v[12:15], v[150:153], v[220:223], v[12:15]
	v_mfma_f32_16x16x32_bf16 v[8:11], v[168:171], v[220:223], v[8:11]
	s_setprio 0
	s_setprio 1
	v_mfma_f32_16x16x32_bf16 v[52:55], v[172:175], v[192:195], v[52:55]
	v_mfma_f32_16x16x32_bf16 v[48:51], v[180:183], v[192:195], v[48:51]
	v_mfma_f32_16x16x32_bf16 v[36:39], v[172:175], v[200:203], v[36:39]
	v_mfma_f32_16x16x32_bf16 v[32:35], v[180:183], v[200:203], v[32:35]
	v_mfma_f32_16x16x32_bf16 v[20:23], v[172:175], v[208:211], v[20:23]
	v_mfma_f32_16x16x32_bf16 v[16:19], v[180:183], v[208:211], v[16:19]
	v_mfma_f32_16x16x32_bf16 v[4:7], v[172:175], v[216:219], v[4:7]
	v_mfma_f32_16x16x32_bf16 v[0:3], v[180:183], v[216:219], v[0:3]
	v_mfma_f32_16x16x32_bf16 v[52:55], v[176:179], v[196:199], v[52:55]
	v_mfma_f32_16x16x32_bf16 v[48:51], v[188:191], v[196:199], v[48:51]
	v_mfma_f32_16x16x32_bf16 v[36:39], v[176:179], v[204:207], v[36:39]
	v_mfma_f32_16x16x32_bf16 v[32:35], v[188:191], v[204:207], v[32:35]
	v_mfma_f32_16x16x32_bf16 v[20:23], v[176:179], v[212:215], v[20:23]
	v_mfma_f32_16x16x32_bf16 v[16:19], v[188:191], v[212:215], v[16:19]
	v_mfma_f32_16x16x32_bf16 v[4:7], v[176:179], v[220:223], v[4:7]
	v_mfma_f32_16x16x32_bf16 v[0:3], v[188:191], v[220:223], v[0:3]
	s_setprio 0
	s_barrier
	s_add_i32 s46, s46, 2
	s_add_u32 s22, s22, 0x100
	s_addc_u32 s23, s23, 0
	s_add_u32 s44, s44, 0x100
	s_addc_u32 s45, s45, 0
	s_cmp_gt_u32 s46, 13
	s_cbranch_scc0 .LBB0_572
	s_and_b64 vcc, exec, s[10:11]
	s_cbranch_vccz .LBB0_575
.LBB0_575:
	s_lshl_b32 s7, s6, 8
	s_lshl_b32 s13, s20, 8
	s_and_b32 s7, s7, 0x3f00
	s_and_b32 s13, s13, 0x700
	v_readlane_b32 s100, v236, 50
	v_readlane_b32 s101, v236, 51
	s_cmp_gt_i32 s6, 63
	s_cselect_b32 s15, s41, 0x1a00
	v_or_b32_e32 v150, s13, v158
	v_add_u32_e32 v148, s7, v156
	v_add_u32_e32 v136, s15, v150
	v_mul_u32_u24_e32 v146, 0x4400, v148
	v_lshl_add_u32 v136, v136, 1, v146
	v_lshlrev_b32_e32 v146, 12, v148
	v_lshl_add_u32 v146, v150, 1, v146
	v_mov_b32_e32 v147, v146
	s_nop 0
	s_cbranch_scc1 .Lp4epi_br1
; __device__ __forceinline__ unsigned cvt_pk_bf16(float lo, float hi) { unsigned r; asm volatile("v_cvt_pk_bf16_f32 %0, %1, %2" : "=v"(r) : "v"(lo), "v"(hi)); return r; }
; __device__ __forceinline__ float bflo(unsigned w) { return __uint_as_float(w << 16); }
; __device__ __forceinline__ float bfhi(unsigned w) { return __uint_as_float(w & 0xffff0000u); }
;     __device__ __forceinline__ void operator()(const f32x4 (&acc)[2][2][4][2], const Unit& u, int wr, int wc, int fr, int fq) const {
;     ...
; #pragma unroll
;         for (int ai = 0; ai < 2; ++ai)
; #pragma unroll
;             for (int m = 0; m < 4; ++m) { const size_t row = (size_t)(row0 + ai * HALF + m * 16);
; #pragma unroll
;                 for (int bj = 0; bj < 2; ++bj) {
;                     const u32x4 g = *(const u32x4*)(P + row * PLD + gcol + bj * HALF);
;                     bf16_t* mp = MG + row * 2048 + col0 + bj * HALF;
;                     float v[8];
;                     v[0] = acc[ai][bj][m][0][0] * bflo(g.x); v[1] = acc[ai][bj][m][0][1] * bfhi(g.x); v[2] = acc[ai][bj][m][0][2] * bflo(g.y); v[3] = acc[ai][bj][m][0][3] * bfhi(g.y);
;                     v[4] = acc[ai][bj][m][1][0] * bflo(g.z); v[5] = acc[ai][bj][m][1][1] * bfhi(g.z); v[6] = acc[ai][bj][m][1][2] * bflo(g.w); v[7] = acc[ai][bj][m][1][3] * bfhi(g.w);
;                     if (br) { const u32x4 p = *(const u32x4*)mp;
;                         v[0] += bflo(p.x); v[1] += bfhi(p.x); v[2] += bflo(p.y); v[3] += bfhi(p.y); v[4] += bflo(p.z); v[5] += bfhi(p.z); v[6] += bflo(p.w); v[7] += bfhi(p.w); }
;                     u32x4 w; w.x = cvt_pk_bf16(v[0], v[1]); w.y = cvt_pk_bf16(v[2], v[3]); w.z = cvt_pk_bf16(v[4], v[5]); w.w = cvt_pk_bf16(v[6], v[7]);
;                     *(u32x4*)mp = w; } }
	global_load_dwordx4 v[164:167], v136, s[72:73]
	global_load_dwordx4 v[172:175], v136, s[72:73] offset:256
	v_add_u32_e32 v136, 0x44000, v136
	global_load_dwordx4 v[192:195], v136, s[72:73]
	global_load_dwordx4 v[200:203], v136, s[72:73] offset:256
	v_add_u32_e32 v136, 0x44000, v136
	global_load_dwordx4 v[208:211], v136, s[72:73]
	global_load_dwordx4 v[216:219], v136, s[72:73] offset:256
	v_add_u32_e32 v136, 0x44000, v136
	global_load_dwordx4 v[180:183], v136, s[72:73]
	s_waitcnt vmcnt(6)
	v_lshlrev_b32_e32 v148, 16, v164
	v_and_b32_e32 v149, 0xffff0000, v164
	v_lshlrev_b32_e32 v150, 16, v165
	v_and_b32_e32 v151, 0xffff0000, v165
	v_lshlrev_b32_e32 v152, 16, v166
	v_and_b32_e32 v153, 0xffff0000, v166
	v_lshlrev_b32_e32 v154, 16, v167
	v_and_b32_e32 v155, 0xffff0000, v167
	v_pk_mul_f32 v[124:125], v[124:125], v[148:149]
	v_pk_mul_f32 v[126:127], v[126:127], v[150:151]
	v_pk_mul_f32 v[120:121], v[120:121], v[152:153]
	v_pk_mul_f32 v[122:123], v[122:123], v[154:155]
	v_cvt_pk_bf16_f32 v164, v124, v125
	v_cvt_pk_bf16_f32 v165, v126, v127
	v_cvt_pk_bf16_f32 v166, v120, v121
	v_cvt_pk_bf16_f32 v167, v122, v123
	global_store_dwordx4 v147, v[164:167], s[100:101]
	s_nop 1
	global_load_dwordx4 v[164:167], v136, s[72:73] offset:256
	v_add_u32_e32 v136, 0x154000, v136
	s_waitcnt vmcnt(7)
	v_lshlrev_b32_e32 v148, 16, v172
	v_and_b32_e32 v149, 0xffff0000, v172
	v_lshlrev_b32_e32 v150, 16, v173
	v_and_b32_e32 v151, 0xffff0000, v173
	v_lshlrev_b32_e32 v152, 16, v174
	v_and_b32_e32 v153, 0xffff0000, v174
	v_lshlrev_b32_e32 v154, 16, v175
	v_and_b32_e32 v155, 0xffff0000, v175
	v_pk_mul_f32 v[116:117], v[116:117], v[148:149]
	v_pk_mul_f32 v[118:119], v[118:119], v[150:151]
	v_pk_mul_f32 v[112:113], v[112:113], v[152:153]
	v_pk_mul_f32 v[114:115], v[114:115], v[154:155]
	v_cvt_pk_bf16_f32 v172, v116, v117
	v_cvt_pk_bf16_f32 v173, v118, v119
	v_cvt_pk_bf16_f32 v174, v112, v113
	v_cvt_pk_bf16_f32 v175, v114, v115
	global_store_dwordx4 v147, v[172:175], s[100:101] offset:256
	v_add_u32_e32 v147, 0x10000, v147
	s_nop 1
	global_load_dwordx4 v[172:175], v136, s[72:73]
	s_waitcnt vmcnt(8)
	v_lshlrev_b32_e32 v148, 16, v192
	v_and_b32_e32 v149, 0xffff0000, v192
	v_lshlrev_b32_e32 v150, 16, v193
	v_and_b32_e32 v151, 0xffff0000, v193
	v_lshlrev_b32_e32 v152, 16, v194
	v_and_b32_e32 v153, 0xffff0000, v194
	v_lshlrev_b32_e32 v154, 16, v195
	v_and_b32_e32 v155, 0xffff0000, v195
	v_pk_mul_f32 v[108:109], v[108:109], v[148:149]
	v_pk_mul_f32 v[110:111], v[110:111], v[150:151]
	v_pk_mul_f32 v[104:105], v[104:105], v[152:153]
	v_pk_mul_f32 v[106:107], v[106:107], v[154:155]
	v_cvt_pk_bf16_f32 v192, v108, v109
	v_cvt_pk_bf16_f32 v193, v110, v111
	v_cvt_pk_bf16_f32 v194, v104, v105
	v_cvt_pk_bf16_f32 v195, v106, v107
	global_store_dwordx4 v147, v[192:195], s[100:101]
	s_nop 1
	global_load_dwordx4 v[192:195], v136, s[72:73] offset:256
	v_add_u32_e32 v136, 0x44000, v136
	s_waitcnt vmcnt(9)
	v_lshlrev_b32_e32 v148, 16, v200
	v_and_b32_e32 v149, 0xffff0000, v200
	v_lshlrev_b32_e32 v150, 16, v201
	v_and_b32_e32 v151, 0xffff0000, v201
	v_lshlrev_b32_e32 v152, 16, v202
	v_and_b32_e32 v153, 0xffff0000, v202
	v_lshlrev_b32_e32 v154, 16, v203
	v_and_b32_e32 v155, 0xffff0000, v203
	v_pk_mul_f32 v[100:101], v[100:101], v[148:149]
	v_pk_mul_f32 v[102:103], v[102:103], v[150:151]
	v_pk_mul_f32 v[96:97], v[96:97], v[152:153]
	v_pk_mul_f32 v[98:99], v[98:99], v[154:155]
	v_cvt_pk_bf16_f32 v200, v100, v101
	v_cvt_pk_bf16_f32 v201, v102, v103
	v_cvt_pk_bf16_f32 v202, v96, v97
	v_cvt_pk_bf16_f32 v203, v98, v99
	global_store_dwordx4 v147, v[200:203], s[100:101] offset:256
	v_add_u32_e32 v147, 0x10000, v147
	s_nop 1
	global_load_dwordx4 v[200:203], v136, s[72:73]
	s_waitcnt vmcnt(10)
	v_lshlrev_b32_e32 v148, 16, v208
	v_and_b32_e32 v149, 0xffff0000, v208
	v_lshlrev_b32_e32 v150, 16, v209
	v_and_b32_e32 v151, 0xffff0000, v209
	v_lshlrev_b32_e32 v152, 16, v210
	v_and_b32_e32 v153, 0xffff0000, v210
	v_lshlrev_b32_e32 v154, 16, v211
	v_and_b32_e32 v155, 0xffff0000, v211
	v_pk_mul_f32 v[92:93], v[92:93], v[148:149]
	v_pk_mul_f32 v[94:95], v[94:95], v[150:151]
	v_pk_mul_f32 v[88:89], v[88:89], v[152:153]
	v_pk_mul_f32 v[90:91], v[90:91], v[154:155]
	v_cvt_pk_bf16_f32 v208, v92, v93
	v_cvt_pk_bf16_f32 v209, v94, v95
	v_cvt_pk_bf16_f32 v210, v88, v89
	v_cvt_pk_bf16_f32 v211, v90, v91
	global_store_dwordx4 v147, v[208:211], s[100:101]
	s_nop 1
	global_load_dwordx4 v[208:211], v136, s[72:73] offset:256
	v_add_u32_e32 v136, 0x44000, v136
	s_waitcnt vmcnt(11)
	v_lshlrev_b32_e32 v148, 16, v216
	v_and_b32_e32 v149, 0xffff0000, v216
	v_lshlrev_b32_e32 v150, 16, v217
	v_and_b32_e32 v151, 0xffff0000, v217
	v_lshlrev_b32_e32 v152, 16, v218
	v_and_b32_e32 v153, 0xffff0000, v218
	v_lshlrev_b32_e32 v154, 16, v219
	v_and_b32_e32 v155, 0xffff0000, v219
	v_pk_mul_f32 v[84:85], v[84:85], v[148:149]
	v_pk_mul_f32 v[86:87], v[86:87], v[150:151]
	v_pk_mul_f32 v[80:81], v[80:81], v[152:153]
	v_pk_mul_f32 v[82:83], v[82:83], v[154:155]
	v_cvt_pk_bf16_f32 v216, v84, v85
	v_cvt_pk_bf16_f32 v217, v86, v87
	v_cvt_pk_bf16_f32 v218, v80, v81
	v_cvt_pk_bf16_f32 v219, v82, v83
	global_store_dwordx4 v147, v[216:219], s[100:101] offset:256
	v_add_u32_e32 v147, 0x10000, v147
	s_nop 1
	global_load_dwordx4 v[216:219], v136, s[72:73]
	s_waitcnt vmcnt(12)
	v_lshlrev_b32_e32 v148, 16, v180
	v_and_b32_e32 v149, 0xffff0000, v180
	v_lshlrev_b32_e32 v150, 16, v181
	v_and_b32_e32 v151, 0xffff0000, v181
	v_lshlrev_b32_e32 v152, 16, v182
	v_and_b32_e32 v153, 0xffff0000, v182
	v_lshlrev_b32_e32 v154, 16, v183
	v_and_b32_e32 v155, 0xffff0000, v183
	v_pk_mul_f32 v[76:77], v[76:77], v[148:149]
	v_pk_mul_f32 v[78:79], v[78:79], v[150:151]
	v_pk_mul_f32 v[72:73], v[72:73], v[152:153]
	v_pk_mul_f32 v[74:75], v[74:75], v[154:155]
	v_cvt_pk_bf16_f32 v180, v76, v77
	v_cvt_pk_bf16_f32 v181, v78, v79
	v_cvt_pk_bf16_f32 v182, v72, v73
	v_cvt_pk_bf16_f32 v183, v74, v75
	global_store_dwordx4 v147, v[180:183], s[100:101]
	s_nop 1
	global_load_dwordx4 v[180:183], v136, s[72:73] offset:256
	v_add_u32_e32 v136, 0x44000, v136
	s_waitcnt vmcnt(12)
; __device__ __forceinline__ unsigned cvt_pk_bf16(float lo, float hi) { unsigned r; asm volatile("v_cvt_pk_bf16_f32 %0, %1, %2" : "=v"(r) : "v"(lo), "v"(hi)); return r; }
; __device__ __forceinline__ float bflo(unsigned w) { return __uint_as_float(w << 16); }
; __device__ __forceinline__ float bfhi(unsigned w) { return __uint_as_float(w & 0xffff0000u); }
;     __device__ __forceinline__ void operator()(const f32x4 (&acc)[2][2][4][2], const Unit& u, int wr, int wc, int fr, int fq) const {
;     ...
; #pragma unroll
;         for (int ai = 0; ai < 2; ++ai)
; #pragma unroll
;             for (int m = 0; m < 4; ++m) { const size_t row = (size_t)(row0 + ai * HALF + m * 16);
; #pragma unroll
;                 for (int bj = 0; bj < 2; ++bj) {
;                     const u32x4 g = *(const u32x4*)(P + row * PLD + gcol + bj * HALF);
;                     bf16_t* mp = MG + row * 2048 + col0 + bj * HALF;
;                     float v[8];
;                     v[0] = acc[ai][bj][m][0][0] * bflo(g.x); v[1] = acc[ai][bj][m][0][1] * bfhi(g.x); v[2] = acc[ai][bj][m][0][2] * bflo(g.y); v[3] = acc[ai][bj][m][0][3] * bfhi(g.y);
;                     v[4] = acc[ai][bj][m][1][0] * bflo(g.z); v[5] = acc[ai][bj][m][1][1] * bfhi(g.z); v[6] = acc[ai][bj][m][1][2] * bflo(g.w); v[7] = acc[ai][bj][m][1][3] * bfhi(g.w);
;                     if (br) { const u32x4 p = *(const u32x4*)mp;
;                         v[0] += bflo(p.x); v[1] += bfhi(p.x); v[2] += bflo(p.y); v[3] += bfhi(p.y); v[4] += bflo(p.z); v[5] += bfhi(p.z); v[6] += bflo(p.w); v[7] += bfhi(p.w); }
;                     u32x4 w; w.x = cvt_pk_bf16(v[0], v[1]); w.y = cvt_pk_bf16(v[2], v[3]); w.z = cvt_pk_bf16(v[4], v[5]); w.w = cvt_pk_bf16(v[6], v[7]);
;                     *(u32x4*)mp = w; } }
	v_lshlrev_b32_e32 v148, 16, v164
	v_and_b32_e32 v149, 0xffff0000, v164
	v_lshlrev_b32_e32 v150, 16, v165
	v_and_b32_e32 v151, 0xffff0000, v165
	v_lshlrev_b32_e32 v152, 16, v166
	v_and_b32_e32 v153, 0xffff0000, v166
	v_lshlrev_b32_e32 v154, 16, v167
	v_and_b32_e32 v155, 0xffff0000, v167
	v_pk_mul_f32 v[68:69], v[68:69], v[148:149]
	v_pk_mul_f32 v[70:71], v[70:71], v[150:151]
	v_pk_mul_f32 v[64:65], v[64:65], v[152:153]
	v_pk_mul_f32 v[66:67], v[66:67], v[154:155]
	v_cvt_pk_bf16_f32 v164, v68, v69
	v_cvt_pk_bf16_f32 v165, v70, v71
	v_cvt_pk_bf16_f32 v166, v64, v65
	v_cvt_pk_bf16_f32 v167, v66, v67
	global_store_dwordx4 v147, v[164:167], s[100:101] offset:256
	v_add_u32_e32 v147, 0x50000, v147
	s_nop 1
	global_load_dwordx4 v[164:167], v136, s[72:73]
	s_waitcnt vmcnt(12)
	v_lshlrev_b32_e32 v148, 16, v172
	v_and_b32_e32 v149, 0xffff0000, v172
	v_lshlrev_b32_e32 v150, 16, v173
	v_and_b32_e32 v151, 0xffff0000, v173
	v_lshlrev_b32_e32 v152, 16, v174
	v_and_b32_e32 v153, 0xffff0000, v174
	v_lshlrev_b32_e32 v154, 16, v175
	v_and_b32_e32 v155, 0xffff0000, v175
	v_pk_mul_f32 v[60:61], v[60:61], v[148:149]
	v_pk_mul_f32 v[62:63], v[62:63], v[150:151]
	v_pk_mul_f32 v[56:57], v[56:57], v[152:153]
	v_pk_mul_f32 v[58:59], v[58:59], v[154:155]
	v_cvt_pk_bf16_f32 v172, v60, v61
	v_cvt_pk_bf16_f32 v173, v62, v63
	v_cvt_pk_bf16_f32 v174, v56, v57
	v_cvt_pk_bf16_f32 v175, v58, v59
	global_store_dwordx4 v147, v[172:175], s[100:101]
	s_nop 1
	global_load_dwordx4 v[172:175], v136, s[72:73] offset:256
	s_waitcnt vmcnt(12)
	v_lshlrev_b32_e32 v148, 16, v192
	v_and_b32_e32 v149, 0xffff0000, v192
	v_lshlrev_b32_e32 v150, 16, v193
	v_and_b32_e32 v151, 0xffff0000, v193
	v_lshlrev_b32_e32 v152, 16, v194
	v_and_b32_e32 v153, 0xffff0000, v194
	v_lshlrev_b32_e32 v154, 16, v195
	v_and_b32_e32 v155, 0xffff0000, v195
	v_pk_mul_f32 v[52:53], v[52:53], v[148:149]
	v_pk_mul_f32 v[54:55], v[54:55], v[150:151]
	v_pk_mul_f32 v[48:49], v[48:49], v[152:153]
	v_pk_mul_f32 v[50:51], v[50:51], v[154:155]
	v_cvt_pk_bf16_f32 v192, v52, v53
	v_cvt_pk_bf16_f32 v193, v54, v55
	v_cvt_pk_bf16_f32 v194, v48, v49
	v_cvt_pk_bf16_f32 v195, v50, v51
	global_store_dwordx4 v147, v[192:195], s[100:101] offset:256
	v_add_u32_e32 v147, 0x10000, v147
	s_waitcnt vmcnt(11)
	v_lshlrev_b32_e32 v148, 16, v200
	v_and_b32_e32 v149, 0xffff0000, v200
	v_lshlrev_b32_e32 v150, 16, v201
	v_and_b32_e32 v151, 0xffff0000, v201
	v_lshlrev_b32_e32 v152, 16, v202
	v_and_b32_e32 v153, 0xffff0000, v202
	v_lshlrev_b32_e32 v154, 16, v203
	v_and_b32_e32 v155, 0xffff0000, v203
	v_pk_mul_f32 v[44:45], v[44:45], v[148:149]
	v_pk_mul_f32 v[46:47], v[46:47], v[150:151]
	v_pk_mul_f32 v[40:41], v[40:41], v[152:153]
	v_pk_mul_f32 v[42:43], v[42:43], v[154:155]
	v_cvt_pk_bf16_f32 v200, v44, v45
	v_cvt_pk_bf16_f32 v201, v46, v47
	v_cvt_pk_bf16_f32 v202, v40, v41
	v_cvt_pk_bf16_f32 v203, v42, v43
	global_store_dwordx4 v147, v[200:203], s[100:101]
	s_waitcnt vmcnt(10)
	v_lshlrev_b32_e32 v148, 16, v208
	v_and_b32_e32 v149, 0xffff0000, v208
	v_lshlrev_b32_e32 v150, 16, v209
	v_and_b32_e32 v151, 0xffff0000, v209
	v_lshlrev_b32_e32 v152, 16, v210
	v_and_b32_e32 v153, 0xffff0000, v210
	v_lshlrev_b32_e32 v154, 16, v211
	v_and_b32_e32 v155, 0xffff0000, v211
	v_pk_mul_f32 v[36:37], v[36:37], v[148:149]
	v_pk_mul_f32 v[38:39], v[38:39], v[150:151]
	v_pk_mul_f32 v[32:33], v[32:33], v[152:153]
	v_pk_mul_f32 v[34:35], v[34:35], v[154:155]
	v_cvt_pk_bf16_f32 v208, v36, v37
	v_cvt_pk_bf16_f32 v209, v38, v39
	v_cvt_pk_bf16_f32 v210, v32, v33
	v_cvt_pk_bf16_f32 v211, v34, v35
	global_store_dwordx4 v147, v[208:211], s[100:101] offset:256
	v_add_u32_e32 v147, 0x10000, v147
	s_waitcnt vmcnt(9)
	v_lshlrev_b32_e32 v148, 16, v216
	v_and_b32_e32 v149, 0xffff0000, v216
	v_lshlrev_b32_e32 v150, 16, v217
	v_and_b32_e32 v151, 0xffff0000, v217
	v_lshlrev_b32_e32 v152, 16, v218
	v_and_b32_e32 v153, 0xffff0000, v218
	v_lshlrev_b32_e32 v154, 16, v219
	v_and_b32_e32 v155, 0xffff0000, v219
	v_pk_mul_f32 v[28:29], v[28:29], v[148:149]
	v_pk_mul_f32 v[30:31], v[30:31], v[150:151]
	v_pk_mul_f32 v[24:25], v[24:25], v[152:153]
	v_pk_mul_f32 v[26:27], v[26:27], v[154:155]
	v_cvt_pk_bf16_f32 v216, v28, v29
	v_cvt_pk_bf16_f32 v217, v30, v31
	v_cvt_pk_bf16_f32 v218, v24, v25
	v_cvt_pk_bf16_f32 v219, v26, v27
	global_store_dwordx4 v147, v[216:219], s[100:101]
	s_waitcnt vmcnt(8)
	v_lshlrev_b32_e32 v148, 16, v180
	v_and_b32_e32 v149, 0xffff0000, v180
	v_lshlrev_b32_e32 v150, 16, v181
	v_and_b32_e32 v151, 0xffff0000, v181
	v_lshlrev_b32_e32 v152, 16, v182
	v_and_b32_e32 v153, 0xffff0000, v182
	v_lshlrev_b32_e32 v154, 16, v183
	v_and_b32_e32 v155, 0xffff0000, v183
	v_pk_mul_f32 v[20:21], v[20:21], v[148:149]
	v_pk_mul_f32 v[22:23], v[22:23], v[150:151]
	v_pk_mul_f32 v[16:17], v[16:17], v[152:153]
	v_pk_mul_f32 v[18:19], v[18:19], v[154:155]
	v_cvt_pk_bf16_f32 v180, v20, v21
	v_cvt_pk_bf16_f32 v181, v22, v23
	v_cvt_pk_bf16_f32 v182, v16, v17
	v_cvt_pk_bf16_f32 v183, v18, v19
	global_store_dwordx4 v147, v[180:183], s[100:101] offset:256
	v_add_u32_e32 v147, 0x10000, v147
	s_waitcnt vmcnt(7)
	v_lshlrev_b32_e32 v148, 16, v164
	v_and_b32_e32 v149, 0xffff0000, v164
	v_lshlrev_b32_e32 v150, 16, v165
	v_and_b32_e32 v151, 0xffff0000, v165
	v_lshlrev_b32_e32 v152, 16, v166
	v_and_b32_e32 v153, 0xffff0000, v166
	v_lshlrev_b32_e32 v154, 16, v167
	v_and_b32_e32 v155, 0xffff0000, v167
	v_pk_mul_f32 v[12:13], v[12:13], v[148:149]
	v_pk_mul_f32 v[14:15], v[14:15], v[150:151]
	v_pk_mul_f32 v[8:9], v[8:9], v[152:153]
	v_pk_mul_f32 v[10:11], v[10:11], v[154:155]
	v_cvt_pk_bf16_f32 v164, v12, v13
	v_cvt_pk_bf16_f32 v165, v14, v15
	v_cvt_pk_bf16_f32 v166, v8, v9
	v_cvt_pk_bf16_f32 v167, v10, v11
	global_store_dwordx4 v147, v[164:167], s[100:101]
	s_waitcnt vmcnt(6)
	v_lshlrev_b32_e32 v148, 16, v172
	v_and_b32_e32 v149, 0xffff0000, v172
	v_lshlrev_b32_e32 v150, 16, v173
	v_and_b32_e32 v151, 0xffff0000, v173
	v_lshlrev_b32_e32 v152, 16, v174
	v_and_b32_e32 v153, 0xffff0000, v174
	v_lshlrev_b32_e32 v154, 16, v175
	v_and_b32_e32 v155, 0xffff0000, v175
	v_pk_mul_f32 v[4:5], v[4:5], v[148:149]
	v_pk_mul_f32 v[6:7], v[6:7], v[150:151]
	v_pk_mul_f32 v[0:1], v[0:1], v[152:153]
	v_pk_mul_f32 v[2:3], v[2:3], v[154:155]
	v_cvt_pk_bf16_f32 v172, v4, v5
	v_cvt_pk_bf16_f32 v173, v6, v7
	v_cvt_pk_bf16_f32 v174, v0, v1
	v_cvt_pk_bf16_f32 v175, v2, v3
	global_store_dwordx4 v147, v[172:175], s[100:101] offset:256
	s_branch .Lp4epi_done

; #define PG8_WAIT_V(n) asm volatile("s_waitcnt vmcnt(" #n ")" ::: "memory")
; #define PG8_BAR __builtin_amdgcn_s_barrier()
; template <class Epi, class Sched, bool ALIGN_EPI = false, bool SP2 = false>
; __device__ __forceinline__ void gemm_phase(PG8_LAS unsigned char* lds, const Gemm g, const Sched& S, const Epi& E) {
;     ...
;         cur = nxt; cA = nA; cB = nB; ++ui;
;         if constexpr (ALIGN_EPI) { if (wr == 1) PG8_BAR; }
;     }
;     PG8_WAIT_V(0);
;     if constexpr (!ALIGN_EPI) { if (wr == 0) PG8_BAR; }
.Lp4epi_done:
	s_andn2_b64 vcc, exec, s[4:5]
	s_mov_b64 s[4:5], -1
	s_cbranch_vccnz .LBB0_564
	s_andn2_b64 vcc, exec, s[2:3]
	s_cbranch_vccnz .LBB0_563
	s_branch .LBB0_563
.LBB0_610:
	s_waitcnt vmcnt(0)
	s_and_b64 vcc, exec, s[10:11]
	s_cbranch_vccz .Lnoalign_p4
	s_barrier

; __device__ __forceinline__ unsigned cvt_pk_bf16(float lo, float hi) { unsigned r; asm volatile("v_cvt_pk_bf16_f32 %0, %1, %2" : "=v"(r) : "v"(lo), "v"(hi)); return r; }
;     __device__ __forceinline__ void operator()(const f32x4 (&acc)[2][2][4][2], const Unit& u, int wr, int wc, int fr, int fq) const {
;         const int row0 = u.pm * BM + wr * 64 + fr, col0 = u.pn * BM + wc * 32 + 4 * fq, b = (u.pm * BM) >> 12;
;         f32x4 gv[2][2], Gv[2][2];
; #pragma unroll
;         for (int bj = 0; bj < 2; ++bj)
; #pragma unroll
;             for (int n = 0; n < 2; ++n) { const int c = col0 + bj * HALF + n * 16; gv[bj][n] = *(const f32x4*)(mod + (size_t)b * 12288 + 2 * 2048 + c);
;                 Gv[bj][n] = *(const f32x4*)(g2 + c) * (*(const f32x4*)(mod + (size_t)b * 12288 + 4 * 2048 + c) + 1.0f); }
;         float* prow = part + (size_t)(u.pn * 4 + wc) * 16384;
; #pragma unroll
;         for (int ai = 0; ai < 2; ++ai)
; #pragma unroll
;             for (int m = 0; m < 4; ++m) { const int row = row0 + ai * HALF + m * 16; const size_t off = (size_t)row * 2048 + col0; float ss = 0.f;
; #pragma unroll
;                 for (int bj = 0; bj < 2; ++bj)
; #pragma unroll
;                     for (int n = 0; n < 2; ++n) { const f32x4 bs = __builtin_nontemporal_load((const f32x4*)(base + off + bj * HALF + n * 16)); const f32x4 x1 = bs + gv[bj][n] * acc[ai][bj][m][n];
;                         *(f32x4*)(out + off + bj * HALF + n * 16) = x1; ss += (x1.x * x1.x + x1.y * x1.y) + (x1.z * x1.z + x1.w * x1.w);
;                         const f32x4 hh = x1 * Gv[bj][n]; u32x2 w; w.x = cvt_pk_bf16(hh.x, hh.y); w.y = cvt_pk_bf16(hh.z, hh.w); *(u32x2*)(A2 + off + bj * HALF + n * 16) = w; }
.LBB0_897:
	v_readlane_b32 s98, v236, 7
	v_readlane_b32 s99, v236, 8
	v_readlane_b32 s76, v236, 35
	v_readlane_b32 s77, v236, 36
	s_ashr_i32 s25, s36, 4
	s_mul_hi_i32 s27, s25, 0xc000
	s_mul_i32 s25, s25, 0xc000
	s_add_u32 s38, s68, s25
	s_addc_u32 s39, s69, s27
	s_add_u32 s40, s38, 0x8000
	s_addc_u32 s41, s39, 0
	s_add_u32 s38, s38, 0x4000
	s_addc_u32 s39, s39, 0
	v_lshl_add_u32 v164, s36, 8, v166
	v_lshl_or_b32 v165, s34, 8, v168
	v_lshlrev_b32_e32 v173, 2, v165
	v_xor_b32_e32 v216, 16, v172
	v_xor_b32_e32 v217, 32, v172
	v_lshlrev_b32_e32 v216, 2, v216
	v_lshlrev_b32_e32 v217, 2, v217
	global_load_dwordx4 v[72:75], v173, s[38:39]
	global_load_dwordx4 v[84:87], v173, s[38:39] offset:64
	global_load_dwordx4 v[92:95], v173, s[38:39] offset:512
	global_load_dwordx4 v[96:99], v173, s[38:39] offset:576
	global_load_dwordx4 v[156:159], v173, s[40:41]
	global_load_dwordx4 v[160:163], v173, s[40:41] offset:64
	global_load_dwordx4 v[174:177], v173, s[40:41] offset:512
	global_load_dwordx4 v[178:181], v173, s[40:41] offset:576
	global_load_dwordx4 v[182:185], v173, s[76:77]
	global_load_dwordx4 v[188:191], v173, s[76:77] offset:64
	global_load_dwordx4 v[192:195], v173, s[76:77] offset:512
	global_load_dwordx4 v[196:199], v173, s[76:77] offset:576
	v_lshl_add_u32 v164, v164, 13, v173
	v_mov_b32_e32 v165, v164
	v_lshrrev_b32_e32 v173, 1, v164
	global_load_dwordx4 v[200:203], v164, s[98:99] nt
	global_load_dwordx4 v[204:207], v164, s[98:99] offset:64 nt
	global_load_dwordx4 v[208:211], v164, s[98:99] offset:512 nt
	global_load_dwordx4 v[212:215], v164, s[98:99] offset:576 nt
	v_add_u32_e32 v164, 0x20000, v164
	s_waitcnt vmcnt(4)
	v_pk_add_f32 v[156:157], v[156:157], 1.0 op_sel_hi:[1,0]
	v_pk_add_f32 v[158:159], v[158:159], 1.0 op_sel_hi:[1,0]
	v_pk_mul_f32 v[182:183], v[182:183], v[156:157]
	v_pk_mul_f32 v[184:185], v[184:185], v[158:159]
	v_pk_add_f32 v[160:161], v[160:161], 1.0 op_sel_hi:[1,0]
	v_pk_add_f32 v[162:163], v[162:163], 1.0 op_sel_hi:[1,0]
	v_pk_mul_f32 v[188:189], v[188:189], v[160:161]
	v_pk_mul_f32 v[190:191], v[190:191], v[162:163]
	v_pk_add_f32 v[174:175], v[174:175], 1.0 op_sel_hi:[1,0]
	v_pk_add_f32 v[176:177], v[176:177], 1.0 op_sel_hi:[1,0]
	v_pk_mul_f32 v[192:193], v[192:193], v[174:175]
	v_pk_mul_f32 v[194:195], v[194:195], v[176:177]
	v_pk_add_f32 v[178:179], v[178:179], 1.0 op_sel_hi:[1,0]
	v_pk_add_f32 v[180:181], v[180:181], 1.0 op_sel_hi:[1,0]
	v_pk_mul_f32 v[196:197], v[196:197], v[178:179]
	v_pk_mul_f32 v[198:199], v[198:199], v[180:181]
	global_load_dwordx4 v[156:159], v164, s[98:99] nt
	global_load_dwordx4 v[160:163], v164, s[98:99] offset:64 nt
	global_load_dwordx4 v[174:177], v164, s[98:99] offset:512 nt
	global_load_dwordx4 v[178:181], v164, s[98:99] offset:576 nt
	v_add_u32_e32 v164, 0x20000, v164
	s_waitcnt vmcnt(7)
	v_pk_fma_f32 v[200:201], v[140:141], v[72:73], v[200:201]
	v_pk_fma_f32 v[202:203], v[142:143], v[74:75], v[202:203]
	global_store_dwordx4 v165, v[200:203], s[66:67]
	v_pk_mul_f32 v[140:141], v[200:201], v[182:183]
	v_pk_mul_f32 v[142:143], v[202:203], v[184:185]
	v_cvt_pk_bf16_f32 v140, v140, v141
	v_cvt_pk_bf16_f32 v141, v142, v143
	global_store_dwordx2 v173, v[140:141], s[8:9]
	v_mul_f32_e32 v142, v200, v200
	v_fmac_f32_e32 v142, v201, v201
	v_fmac_f32_e32 v142, v202, v202
	v_fmac_f32_e32 v142, v203, v203
	global_load_dwordx4 v[200:203], v164, s[98:99] nt
	s_waitcnt vmcnt(9)
	v_pk_fma_f32 v[204:205], v[136:137], v[84:85], v[204:205]
	v_pk_fma_f32 v[206:207], v[138:139], v[86:87], v[206:207]
	global_store_dwordx4 v165, v[204:207], s[66:67] offset:64
	v_pk_mul_f32 v[136:137], v[204:205], v[188:189]
	v_pk_mul_f32 v[138:139], v[206:207], v[190:191]
	v_cvt_pk_bf16_f32 v136, v136, v137
	v_cvt_pk_bf16_f32 v137, v138, v139
	global_store_dwordx2 v173, v[136:137], s[8:9] offset:32
	v_fmac_f32_e32 v142, v204, v204
	v_fmac_f32_e32 v142, v205, v205
	v_fmac_f32_e32 v142, v206, v206
	v_fmac_f32_e32 v142, v207, v207
	global_load_dwordx4 v[204:207], v164, s[98:99] offset:64 nt
	s_waitcnt vmcnt(11)
	v_pk_fma_f32 v[208:209], v[132:133], v[92:93], v[208:209]
	v_pk_fma_f32 v[210:211], v[134:135], v[94:95], v[210:211]
	global_store_dwordx4 v165, v[208:211], s[66:67] offset:512
	v_pk_mul_f32 v[132:133], v[208:209], v[192:193]
	v_pk_mul_f32 v[134:135], v[210:211], v[194:195]
	v_cvt_pk_bf16_f32 v132, v132, v133
	v_cvt_pk_bf16_f32 v133, v134, v135
	global_store_dwordx2 v173, v[132:133], s[8:9] offset:256
	v_fmac_f32_e32 v142, v208, v208
	v_fmac_f32_e32 v142, v209, v209
	v_fmac_f32_e32 v142, v210, v210
	v_fmac_f32_e32 v142, v211, v211
	global_load_dwordx4 v[208:211], v164, s[98:99] offset:512 nt
	s_waitcnt vmcnt(13)
	v_pk_fma_f32 v[212:213], v[128:129], v[96:97], v[212:213]
	v_pk_fma_f32 v[214:215], v[130:131], v[98:99], v[214:215]
	global_store_dwordx4 v165, v[212:215], s[66:67] offset:576
	v_pk_mul_f32 v[128:129], v[212:213], v[196:197]
	v_pk_mul_f32 v[130:131], v[214:215], v[198:199]
	v_cvt_pk_bf16_f32 v128, v128, v129
	v_cvt_pk_bf16_f32 v129, v130, v131
	global_store_dwordx2 v173, v[128:129], s[8:9] offset:288
	v_fmac_f32_e32 v142, v212, v212
	v_fmac_f32_e32 v142, v213, v213
	v_fmac_f32_e32 v142, v214, v214
	v_fmac_f32_e32 v142, v215, v215
	v_add_u32_e32 v165, 0x20000, v165
	v_lshrrev_b32_e32 v173, 1, v165
	global_load_dwordx4 v[212:215], v164, s[98:99] offset:576 nt
	v_add_u32_e32 v164, 0x20000, v164
	s_waitcnt vmcnt(15)
	v_pk_fma_f32 v[156:157], v[124:125], v[72:73], v[156:157]
	v_pk_fma_f32 v[158:159], v[126:127], v[74:75], v[158:159]
	global_store_dwordx4 v165, v[156:159], s[66:67]
	v_pk_mul_f32 v[124:125], v[156:157], v[182:183]
	v_pk_mul_f32 v[126:127], v[158:159], v[184:185]
	v_cvt_pk_bf16_f32 v124, v124, v125
	v_cvt_pk_bf16_f32 v125, v126, v127
	global_store_dwordx2 v173, v[124:125], s[8:9]
	v_mul_f32_e32 v126, v156, v156
	v_fmac_f32_e32 v126, v157, v157
	v_fmac_f32_e32 v126, v158, v158
	v_fmac_f32_e32 v126, v159, v159
	global_load_dwordx4 v[156:159], v164, s[98:99] nt
	s_waitcnt vmcnt(17)
; __device__ __forceinline__ unsigned cvt_pk_bf16(float lo, float hi) { unsigned r; asm volatile("v_cvt_pk_bf16_f32 %0, %1, %2" : "=v"(r) : "v"(lo), "v"(hi)); return r; }
;     __device__ __forceinline__ void operator()(const f32x4 (&acc)[2][2][4][2], const Unit& u, int wr, int wc, int fr, int fq) const {
;     ...
;         for (int ai = 0; ai < 2; ++ai)
; #pragma unroll
;             for (int m = 0; m < 4; ++m) { const int row = row0 + ai * HALF + m * 16; const size_t off = (size_t)row * 2048 + col0; float ss = 0.f;
; #pragma unroll
;                 for (int bj = 0; bj < 2; ++bj)
; #pragma unroll
;                     for (int n = 0; n < 2; ++n) { const f32x4 bs = __builtin_nontemporal_load((const f32x4*)(base + off + bj * HALF + n * 16)); const f32x4 x1 = bs + gv[bj][n] * acc[ai][bj][m][n];
;                         *(f32x4*)(out + off + bj * HALF + n * 16) = x1; ss += (x1.x * x1.x + x1.y * x1.y) + (x1.z * x1.z + x1.w * x1.w);
;                         const f32x4 hh = x1 * Gv[bj][n]; u32x2 w; w.x = cvt_pk_bf16(hh.x, hh.y); w.y = cvt_pk_bf16(hh.z, hh.w); *(u32x2*)(A2 + off + bj * HALF + n * 16) = w; }
	v_pk_fma_f32 v[160:161], v[120:121], v[84:85], v[160:161]
	v_pk_fma_f32 v[162:163], v[122:123], v[86:87], v[162:163]
	global_store_dwordx4 v165, v[160:163], s[66:67] offset:64
	v_pk_mul_f32 v[120:121], v[160:161], v[188:189]
	v_pk_mul_f32 v[122:123], v[162:163], v[190:191]
	v_cvt_pk_bf16_f32 v120, v120, v121
	v_cvt_pk_bf16_f32 v121, v122, v123
	global_store_dwordx2 v173, v[120:121], s[8:9] offset:32
	v_fmac_f32_e32 v126, v160, v160
	v_fmac_f32_e32 v126, v161, v161
	v_fmac_f32_e32 v126, v162, v162
	v_fmac_f32_e32 v126, v163, v163
	global_load_dwordx4 v[160:163], v164, s[98:99] offset:64 nt
	s_waitcnt vmcnt(19)
	v_pk_fma_f32 v[174:175], v[116:117], v[92:93], v[174:175]
	v_pk_fma_f32 v[176:177], v[118:119], v[94:95], v[176:177]
	global_store_dwordx4 v165, v[174:177], s[66:67] offset:512
	v_pk_mul_f32 v[116:117], v[174:175], v[192:193]
	v_pk_mul_f32 v[118:119], v[176:177], v[194:195]
	v_cvt_pk_bf16_f32 v116, v116, v117
	v_cvt_pk_bf16_f32 v117, v118, v119
	global_store_dwordx2 v173, v[116:117], s[8:9] offset:256
	v_fmac_f32_e32 v126, v174, v174
	v_fmac_f32_e32 v126, v175, v175
	v_fmac_f32_e32 v126, v176, v176
	v_fmac_f32_e32 v126, v177, v177
	global_load_dwordx4 v[174:177], v164, s[98:99] offset:512 nt
	s_waitcnt vmcnt(21)
	v_pk_fma_f32 v[178:179], v[112:113], v[96:97], v[178:179]
	v_pk_fma_f32 v[180:181], v[114:115], v[98:99], v[180:181]
	global_store_dwordx4 v165, v[178:181], s[66:67] offset:576
	v_pk_mul_f32 v[112:113], v[178:179], v[196:197]
	v_pk_mul_f32 v[114:115], v[180:181], v[198:199]
	v_cvt_pk_bf16_f32 v112, v112, v113
	v_cvt_pk_bf16_f32 v113, v114, v115
	global_store_dwordx2 v173, v[112:113], s[8:9] offset:288
	v_fmac_f32_e32 v126, v178, v178
	v_fmac_f32_e32 v126, v179, v179
	v_fmac_f32_e32 v126, v180, v180
	v_fmac_f32_e32 v126, v181, v181
	v_add_u32_e32 v165, 0x20000, v165
	v_lshrrev_b32_e32 v173, 1, v165
	global_load_dwordx4 v[178:181], v164, s[98:99] offset:576 nt
	v_add_u32_e32 v164, 0xa0000, v164
	s_waitcnt vmcnt(21)
	v_pk_fma_f32 v[200:201], v[108:109], v[72:73], v[200:201]
	v_pk_fma_f32 v[202:203], v[110:111], v[74:75], v[202:203]
	global_store_dwordx4 v165, v[200:203], s[66:67]
	v_pk_mul_f32 v[108:109], v[200:201], v[182:183]
	v_pk_mul_f32 v[110:111], v[202:203], v[184:185]
	v_cvt_pk_bf16_f32 v108, v108, v109
	v_cvt_pk_bf16_f32 v109, v110, v111
	global_store_dwordx2 v173, v[108:109], s[8:9]
	v_mul_f32_e32 v110, v200, v200
	v_fmac_f32_e32 v110, v201, v201
	v_fmac_f32_e32 v110, v202, v202
	v_fmac_f32_e32 v110, v203, v203
	global_load_dwordx4 v[200:203], v164, s[98:99] nt
	s_waitcnt vmcnt(21)
	v_pk_fma_f32 v[204:205], v[104:105], v[84:85], v[204:205]
	v_pk_fma_f32 v[206:207], v[106:107], v[86:87], v[206:207]
	global_store_dwordx4 v165, v[204:207], s[66:67] offset:64
	v_pk_mul_f32 v[104:105], v[204:205], v[188:189]
	v_pk_mul_f32 v[106:107], v[206:207], v[190:191]
	v_cvt_pk_bf16_f32 v104, v104, v105
	v_cvt_pk_bf16_f32 v105, v106, v107
	global_store_dwordx2 v173, v[104:105], s[8:9] offset:32
	v_fmac_f32_e32 v110, v204, v204
	v_fmac_f32_e32 v110, v205, v205
	v_fmac_f32_e32 v110, v206, v206
	v_fmac_f32_e32 v110, v207, v207
	global_load_dwordx4 v[204:207], v164, s[98:99] offset:64 nt
	s_waitcnt vmcnt(21)
	v_pk_fma_f32 v[208:209], v[100:101], v[92:93], v[208:209]
	v_pk_fma_f32 v[210:211], v[102:103], v[94:95], v[210:211]
	global_store_dwordx4 v165, v[208:211], s[66:67] offset:512
	v_pk_mul_f32 v[100:101], v[208:209], v[192:193]
	v_pk_mul_f32 v[102:103], v[210:211], v[194:195]
	v_cvt_pk_bf16_f32 v100, v100, v101
	v_cvt_pk_bf16_f32 v101, v102, v103
	global_store_dwordx2 v173, v[100:101], s[8:9] offset:256
	v_fmac_f32_e32 v110, v208, v208
	v_fmac_f32_e32 v110, v209, v209
	v_fmac_f32_e32 v110, v210, v210
	v_fmac_f32_e32 v110, v211, v211
	global_load_dwordx4 v[208:211], v164, s[98:99] offset:512 nt
	s_waitcnt vmcnt(21)
	v_pk_fma_f32 v[212:213], v[88:89], v[96:97], v[212:213]
	v_pk_fma_f32 v[214:215], v[90:91], v[98:99], v[214:215]
	global_store_dwordx4 v165, v[212:215], s[66:67] offset:576
	v_pk_mul_f32 v[88:89], v[212:213], v[196:197]
	v_pk_mul_f32 v[90:91], v[214:215], v[198:199]
	v_cvt_pk_bf16_f32 v88, v88, v89
	v_cvt_pk_bf16_f32 v89, v90, v91
	global_store_dwordx2 v173, v[88:89], s[8:9] offset:288
	v_fmac_f32_e32 v110, v212, v212
	v_fmac_f32_e32 v110, v213, v213
	v_fmac_f32_e32 v110, v214, v214
	v_fmac_f32_e32 v110, v215, v215
	v_add_u32_e32 v165, 0x20000, v165
	v_lshrrev_b32_e32 v173, 1, v165
	global_load_dwordx4 v[212:215], v164, s[98:99] offset:576 nt
	v_add_u32_e32 v164, 0x20000, v164
	s_waitcnt vmcnt(21)
	v_pk_fma_f32 v[156:157], v[80:81], v[72:73], v[156:157]
	v_pk_fma_f32 v[158:159], v[82:83], v[74:75], v[158:159]
	global_store_dwordx4 v165, v[156:159], s[66:67]
	v_pk_mul_f32 v[80:81], v[156:157], v[182:183]
	v_pk_mul_f32 v[82:83], v[158:159], v[184:185]
	v_cvt_pk_bf16_f32 v80, v80, v81
	v_cvt_pk_bf16_f32 v81, v82, v83
	global_store_dwordx2 v173, v[80:81], s[8:9]
	v_mul_f32_e32 v82, v156, v156
	v_fmac_f32_e32 v82, v157, v157
	v_fmac_f32_e32 v82, v158, v158
	v_fmac_f32_e32 v82, v159, v159
	global_load_dwordx4 v[156:159], v164, s[98:99] nt
	s_waitcnt vmcnt(21)
	v_pk_fma_f32 v[160:161], v[76:77], v[84:85], v[160:161]
	v_pk_fma_f32 v[162:163], v[78:79], v[86:87], v[162:163]
	global_store_dwordx4 v165, v[160:163], s[66:67] offset:64
	v_pk_mul_f32 v[76:77], v[160:161], v[188:189]
	v_pk_mul_f32 v[78:79], v[162:163], v[190:191]
	v_cvt_pk_bf16_f32 v76, v76, v77
	v_cvt_pk_bf16_f32 v77, v78, v79
	global_store_dwordx2 v173, v[76:77], s[8:9] offset:32
	v_fmac_f32_e32 v82, v160, v160
	v_fmac_f32_e32 v82, v161, v161
	v_fmac_f32_e32 v82, v162, v162
	v_fmac_f32_e32 v82, v163, v163
	global_load_dwordx4 v[160:163], v164, s[98:99] offset:64 nt
	s_waitcnt vmcnt(21)
; __device__ __forceinline__ unsigned cvt_pk_bf16(float lo, float hi) { unsigned r; asm volatile("v_cvt_pk_bf16_f32 %0, %1, %2" : "=v"(r) : "v"(lo), "v"(hi)); return r; }
;     __device__ __forceinline__ void operator()(const f32x4 (&acc)[2][2][4][2], const Unit& u, int wr, int wc, int fr, int fq) const {
;     ...
;         for (int ai = 0; ai < 2; ++ai)
; #pragma unroll
;             for (int m = 0; m < 4; ++m) { const int row = row0 + ai * HALF + m * 16; const size_t off = (size_t)row * 2048 + col0; float ss = 0.f;
; #pragma unroll
;                 for (int bj = 0; bj < 2; ++bj)
; #pragma unroll
;                     for (int n = 0; n < 2; ++n) { const f32x4 bs = __builtin_nontemporal_load((const f32x4*)(base + off + bj * HALF + n * 16)); const f32x4 x1 = bs + gv[bj][n] * acc[ai][bj][m][n];
;                         *(f32x4*)(out + off + bj * HALF + n * 16) = x1; ss += (x1.x * x1.x + x1.y * x1.y) + (x1.z * x1.z + x1.w * x1.w);
;                         const f32x4 hh = x1 * Gv[bj][n]; u32x2 w; w.x = cvt_pk_bf16(hh.x, hh.y); w.y = cvt_pk_bf16(hh.z, hh.w); *(u32x2*)(A2 + off + bj * HALF + n * 16) = w; }
	v_pk_fma_f32 v[174:175], v[68:69], v[92:93], v[174:175]
	v_pk_fma_f32 v[176:177], v[70:71], v[94:95], v[176:177]
	global_store_dwordx4 v165, v[174:177], s[66:67] offset:512
	v_pk_mul_f32 v[68:69], v[174:175], v[192:193]
	v_pk_mul_f32 v[70:71], v[176:177], v[194:195]
	v_cvt_pk_bf16_f32 v68, v68, v69
	v_cvt_pk_bf16_f32 v69, v70, v71
	global_store_dwordx2 v173, v[68:69], s[8:9] offset:256
	v_fmac_f32_e32 v82, v174, v174
	v_fmac_f32_e32 v82, v175, v175
	v_fmac_f32_e32 v82, v176, v176
	v_fmac_f32_e32 v82, v177, v177
	global_load_dwordx4 v[174:177], v164, s[98:99] offset:512 nt
	s_waitcnt vmcnt(21)
	v_pk_fma_f32 v[178:179], v[64:65], v[96:97], v[178:179]
	v_pk_fma_f32 v[180:181], v[66:67], v[98:99], v[180:181]
	global_store_dwordx4 v165, v[178:181], s[66:67] offset:576
	v_pk_mul_f32 v[64:65], v[178:179], v[196:197]
	v_pk_mul_f32 v[66:67], v[180:181], v[198:199]
	v_cvt_pk_bf16_f32 v64, v64, v65
	v_cvt_pk_bf16_f32 v65, v66, v67
	global_store_dwordx2 v173, v[64:65], s[8:9] offset:288
	v_fmac_f32_e32 v82, v178, v178
	v_fmac_f32_e32 v82, v179, v179
	v_fmac_f32_e32 v82, v180, v180
	v_fmac_f32_e32 v82, v181, v181
	v_add_u32_e32 v165, 0xa0000, v165
	v_lshrrev_b32_e32 v173, 1, v165
	global_load_dwordx4 v[178:181], v164, s[98:99] offset:576 nt
	v_add_u32_e32 v164, 0x20000, v164
	s_waitcnt vmcnt(21)
	v_pk_fma_f32 v[200:201], v[60:61], v[72:73], v[200:201]
	v_pk_fma_f32 v[202:203], v[62:63], v[74:75], v[202:203]
	global_store_dwordx4 v165, v[200:203], s[66:67]
	v_pk_mul_f32 v[60:61], v[200:201], v[182:183]
	v_pk_mul_f32 v[62:63], v[202:203], v[184:185]
	v_cvt_pk_bf16_f32 v60, v60, v61
	v_cvt_pk_bf16_f32 v61, v62, v63
	global_store_dwordx2 v173, v[60:61], s[8:9]
	v_mul_f32_e32 v62, v200, v200
	v_fmac_f32_e32 v62, v201, v201
	v_fmac_f32_e32 v62, v202, v202
	v_fmac_f32_e32 v62, v203, v203
	global_load_dwordx4 v[200:203], v164, s[98:99] nt
	s_waitcnt vmcnt(21)
	v_pk_fma_f32 v[204:205], v[56:57], v[84:85], v[204:205]
	v_pk_fma_f32 v[206:207], v[58:59], v[86:87], v[206:207]
	global_store_dwordx4 v165, v[204:207], s[66:67] offset:64
	v_pk_mul_f32 v[56:57], v[204:205], v[188:189]
	v_pk_mul_f32 v[58:59], v[206:207], v[190:191]
	v_cvt_pk_bf16_f32 v56, v56, v57
	v_cvt_pk_bf16_f32 v57, v58, v59
	global_store_dwordx2 v173, v[56:57], s[8:9] offset:32
	v_fmac_f32_e32 v62, v204, v204
	v_fmac_f32_e32 v62, v205, v205
	v_fmac_f32_e32 v62, v206, v206
	v_fmac_f32_e32 v62, v207, v207
	global_load_dwordx4 v[204:207], v164, s[98:99] offset:64 nt
	s_waitcnt vmcnt(21)
	v_pk_fma_f32 v[208:209], v[52:53], v[92:93], v[208:209]
	v_pk_fma_f32 v[210:211], v[54:55], v[94:95], v[210:211]
	global_store_dwordx4 v165, v[208:211], s[66:67] offset:512
	v_pk_mul_f32 v[52:53], v[208:209], v[192:193]
	v_pk_mul_f32 v[54:55], v[210:211], v[194:195]
	v_cvt_pk_bf16_f32 v52, v52, v53
	v_cvt_pk_bf16_f32 v53, v54, v55
	global_store_dwordx2 v173, v[52:53], s[8:9] offset:256
	v_fmac_f32_e32 v62, v208, v208
	v_fmac_f32_e32 v62, v209, v209
	v_fmac_f32_e32 v62, v210, v210
	v_fmac_f32_e32 v62, v211, v211
	global_load_dwordx4 v[208:211], v164, s[98:99] offset:512 nt
	s_waitcnt vmcnt(21)
	v_pk_fma_f32 v[212:213], v[48:49], v[96:97], v[212:213]
	v_pk_fma_f32 v[214:215], v[50:51], v[98:99], v[214:215]
	global_store_dwordx4 v165, v[212:215], s[66:67] offset:576
	v_pk_mul_f32 v[48:49], v[212:213], v[196:197]
	v_pk_mul_f32 v[50:51], v[214:215], v[198:199]
	v_cvt_pk_bf16_f32 v48, v48, v49
	v_cvt_pk_bf16_f32 v49, v50, v51
	global_store_dwordx2 v173, v[48:49], s[8:9] offset:288
	v_fmac_f32_e32 v62, v212, v212
	v_fmac_f32_e32 v62, v213, v213
	v_fmac_f32_e32 v62, v214, v214
	v_fmac_f32_e32 v62, v215, v215
	v_add_u32_e32 v165, 0x20000, v165
	v_lshrrev_b32_e32 v173, 1, v165
	global_load_dwordx4 v[212:215], v164, s[98:99] offset:576 nt
	v_add_u32_e32 v164, 0x20000, v164
	s_waitcnt vmcnt(21)
	v_pk_fma_f32 v[156:157], v[44:45], v[72:73], v[156:157]
	v_pk_fma_f32 v[158:159], v[46:47], v[74:75], v[158:159]
	global_store_dwordx4 v165, v[156:159], s[66:67]
	v_pk_mul_f32 v[44:45], v[156:157], v[182:183]
	v_pk_mul_f32 v[46:47], v[158:159], v[184:185]
	v_cvt_pk_bf16_f32 v44, v44, v45
	v_cvt_pk_bf16_f32 v45, v46, v47
	global_store_dwordx2 v173, v[44:45], s[8:9]
	v_mul_f32_e32 v46, v156, v156
	v_fmac_f32_e32 v46, v157, v157
	v_fmac_f32_e32 v46, v158, v158
	v_fmac_f32_e32 v46, v159, v159
	global_load_dwordx4 v[156:159], v164, s[98:99] nt
	s_waitcnt vmcnt(21)
	v_pk_fma_f32 v[160:161], v[40:41], v[84:85], v[160:161]
	v_pk_fma_f32 v[162:163], v[42:43], v[86:87], v[162:163]
	global_store_dwordx4 v165, v[160:163], s[66:67] offset:64
	v_pk_mul_f32 v[40:41], v[160:161], v[188:189]
	v_pk_mul_f32 v[42:43], v[162:163], v[190:191]
	v_cvt_pk_bf16_f32 v40, v40, v41
	v_cvt_pk_bf16_f32 v41, v42, v43
	global_store_dwordx2 v173, v[40:41], s[8:9] offset:32
	v_fmac_f32_e32 v46, v160, v160
	v_fmac_f32_e32 v46, v161, v161
	v_fmac_f32_e32 v46, v162, v162
	v_fmac_f32_e32 v46, v163, v163
	global_load_dwordx4 v[160:163], v164, s[98:99] offset:64 nt
	s_waitcnt vmcnt(21)
	v_pk_fma_f32 v[174:175], v[36:37], v[92:93], v[174:175]
	v_pk_fma_f32 v[176:177], v[38:39], v[94:95], v[176:177]
	global_store_dwordx4 v165, v[174:177], s[66:67] offset:512
	v_pk_mul_f32 v[36:37], v[174:175], v[192:193]
	v_pk_mul_f32 v[38:39], v[176:177], v[194:195]
	v_cvt_pk_bf16_f32 v36, v36, v37
	v_cvt_pk_bf16_f32 v37, v38, v39
	global_store_dwordx2 v173, v[36:37], s[8:9] offset:256
	v_fmac_f32_e32 v46, v174, v174
	v_fmac_f32_e32 v46, v175, v175
	v_fmac_f32_e32 v46, v176, v176
	v_fmac_f32_e32 v46, v177, v177
	global_load_dwordx4 v[174:177], v164, s[98:99] offset:512 nt
	s_waitcnt vmcnt(21)
; __device__ __forceinline__ unsigned cvt_pk_bf16(float lo, float hi) { unsigned r; asm volatile("v_cvt_pk_bf16_f32 %0, %1, %2" : "=v"(r) : "v"(lo), "v"(hi)); return r; }
; #define PG8_WAIT_V(n) asm volatile("s_waitcnt vmcnt(" #n ")" ::: "memory")
; #define PG8_BAR __builtin_amdgcn_s_barrier()
;     __device__ __forceinline__ void operator()(const f32x4 (&acc)[2][2][4][2], const Unit& u, int wr, int wc, int fr, int fq) const {
;     ...
;                     for (int n = 0; n < 2; ++n) { const f32x4 bs = __builtin_nontemporal_load((const f32x4*)(base + off + bj * HALF + n * 16)); const f32x4 x1 = bs + gv[bj][n] * acc[ai][bj][m][n];
;                         *(f32x4*)(out + off + bj * HALF + n * 16) = x1; ss += (x1.x * x1.x + x1.y * x1.y) + (x1.z * x1.z + x1.w * x1.w);
;                         const f32x4 hh = x1 * Gv[bj][n]; u32x2 w; w.x = cvt_pk_bf16(hh.x, hh.y); w.y = cvt_pk_bf16(hh.z, hh.w); *(u32x2*)(A2 + off + bj * HALF + n * 16) = w; }
;                 ss += __shfl_xor(ss, 16); ss += __shfl_xor(ss, 32);
;                 if (fq == 0) prow[row] = ss; }
; template <class Epi, class Sched, bool ALIGN_EPI = false, bool SP2 = false>
; __device__ __forceinline__ void gemm_phase(PG8_LAS unsigned char* lds, const Gemm g, const Sched& S, const Epi& E) {
;     ...
;         cur = nxt; cA = nA; cB = nB; ++ui;
;         if constexpr (ALIGN_EPI) { if (wr == 1) PG8_BAR; }
;     }
;     PG8_WAIT_V(0);
;     if constexpr (!ALIGN_EPI) { if (wr == 0) PG8_BAR; }
	v_pk_fma_f32 v[178:179], v[32:33], v[96:97], v[178:179]
	v_pk_fma_f32 v[180:181], v[34:35], v[98:99], v[180:181]
	global_store_dwordx4 v165, v[178:181], s[66:67] offset:576
	v_pk_mul_f32 v[32:33], v[178:179], v[196:197]
	v_pk_mul_f32 v[34:35], v[180:181], v[198:199]
	v_cvt_pk_bf16_f32 v32, v32, v33
	v_cvt_pk_bf16_f32 v33, v34, v35
	global_store_dwordx2 v173, v[32:33], s[8:9] offset:288
	v_fmac_f32_e32 v46, v178, v178
	v_fmac_f32_e32 v46, v179, v179
	v_fmac_f32_e32 v46, v180, v180
	v_fmac_f32_e32 v46, v181, v181
	v_add_u32_e32 v165, 0x20000, v165
	v_lshrrev_b32_e32 v173, 1, v165
	global_load_dwordx4 v[178:181], v164, s[98:99] offset:576 nt
	s_waitcnt vmcnt(21)
	v_pk_fma_f32 v[200:201], v[28:29], v[72:73], v[200:201]
	v_pk_fma_f32 v[202:203], v[30:31], v[74:75], v[202:203]
	global_store_dwordx4 v165, v[200:203], s[66:67]
	v_pk_mul_f32 v[28:29], v[200:201], v[182:183]
	v_pk_mul_f32 v[30:31], v[202:203], v[184:185]
	v_cvt_pk_bf16_f32 v28, v28, v29
	v_cvt_pk_bf16_f32 v29, v30, v31
	global_store_dwordx2 v173, v[28:29], s[8:9]
	v_mul_f32_e32 v30, v200, v200
	v_fmac_f32_e32 v30, v201, v201
	v_fmac_f32_e32 v30, v202, v202
	v_fmac_f32_e32 v30, v203, v203
	s_waitcnt vmcnt(20)
	v_pk_fma_f32 v[204:205], v[24:25], v[84:85], v[204:205]
	v_pk_fma_f32 v[206:207], v[26:27], v[86:87], v[206:207]
	global_store_dwordx4 v165, v[204:207], s[66:67] offset:64
	v_pk_mul_f32 v[24:25], v[204:205], v[188:189]
	v_pk_mul_f32 v[26:27], v[206:207], v[190:191]
	v_cvt_pk_bf16_f32 v24, v24, v25
	v_cvt_pk_bf16_f32 v25, v26, v27
	global_store_dwordx2 v173, v[24:25], s[8:9] offset:32
	v_fmac_f32_e32 v30, v204, v204
	v_fmac_f32_e32 v30, v205, v205
	v_fmac_f32_e32 v30, v206, v206
	v_fmac_f32_e32 v30, v207, v207
	s_waitcnt vmcnt(19)
	v_pk_fma_f32 v[208:209], v[20:21], v[92:93], v[208:209]
	v_pk_fma_f32 v[210:211], v[22:23], v[94:95], v[210:211]
	global_store_dwordx4 v165, v[208:211], s[66:67] offset:512
	v_pk_mul_f32 v[20:21], v[208:209], v[192:193]
	v_pk_mul_f32 v[22:23], v[210:211], v[194:195]
	v_cvt_pk_bf16_f32 v20, v20, v21
	v_cvt_pk_bf16_f32 v21, v22, v23
	global_store_dwordx2 v173, v[20:21], s[8:9] offset:256
	v_fmac_f32_e32 v30, v208, v208
	v_fmac_f32_e32 v30, v209, v209
	v_fmac_f32_e32 v30, v210, v210
	v_fmac_f32_e32 v30, v211, v211
	s_waitcnt vmcnt(18)
	v_pk_fma_f32 v[212:213], v[16:17], v[96:97], v[212:213]
	v_pk_fma_f32 v[214:215], v[18:19], v[98:99], v[214:215]
	global_store_dwordx4 v165, v[212:215], s[66:67] offset:576
	v_pk_mul_f32 v[16:17], v[212:213], v[196:197]
	v_pk_mul_f32 v[18:19], v[214:215], v[198:199]
	v_cvt_pk_bf16_f32 v16, v16, v17
	v_cvt_pk_bf16_f32 v17, v18, v19
	global_store_dwordx2 v173, v[16:17], s[8:9] offset:288
	v_fmac_f32_e32 v30, v212, v212
	v_fmac_f32_e32 v30, v213, v213
	v_fmac_f32_e32 v30, v214, v214
	v_fmac_f32_e32 v30, v215, v215
	v_add_u32_e32 v165, 0x20000, v165
	v_lshrrev_b32_e32 v173, 1, v165
	s_waitcnt vmcnt(17)
	v_pk_fma_f32 v[156:157], v[12:13], v[72:73], v[156:157]
	v_pk_fma_f32 v[158:159], v[14:15], v[74:75], v[158:159]
	global_store_dwordx4 v165, v[156:159], s[66:67]
	v_pk_mul_f32 v[12:13], v[156:157], v[182:183]
	v_pk_mul_f32 v[14:15], v[158:159], v[184:185]
	v_cvt_pk_bf16_f32 v12, v12, v13
	v_cvt_pk_bf16_f32 v13, v14, v15
	global_store_dwordx2 v173, v[12:13], s[8:9]
	v_mul_f32_e32 v14, v156, v156
	v_fmac_f32_e32 v14, v157, v157
	v_fmac_f32_e32 v14, v158, v158
	v_fmac_f32_e32 v14, v159, v159
	s_waitcnt vmcnt(16)
	v_pk_fma_f32 v[160:161], v[8:9], v[84:85], v[160:161]
	v_pk_fma_f32 v[162:163], v[10:11], v[86:87], v[162:163]
	global_store_dwordx4 v165, v[160:163], s[66:67] offset:64
	v_pk_mul_f32 v[8:9], v[160:161], v[188:189]
	v_pk_mul_f32 v[10:11], v[162:163], v[190:191]
	v_cvt_pk_bf16_f32 v8, v8, v9
	v_cvt_pk_bf16_f32 v9, v10, v11
	global_store_dwordx2 v173, v[8:9], s[8:9] offset:32
	v_fmac_f32_e32 v14, v160, v160
	v_fmac_f32_e32 v14, v161, v161
	v_fmac_f32_e32 v14, v162, v162
	v_fmac_f32_e32 v14, v163, v163
	s_waitcnt vmcnt(15)
	v_pk_fma_f32 v[174:175], v[4:5], v[92:93], v[174:175]
	v_pk_fma_f32 v[176:177], v[6:7], v[94:95], v[176:177]
	global_store_dwordx4 v165, v[174:177], s[66:67] offset:512
	v_pk_mul_f32 v[4:5], v[174:175], v[192:193]
	v_pk_mul_f32 v[6:7], v[176:177], v[194:195]
	v_cvt_pk_bf16_f32 v4, v4, v5
	v_cvt_pk_bf16_f32 v5, v6, v7
	global_store_dwordx2 v173, v[4:5], s[8:9] offset:256
	v_fmac_f32_e32 v14, v174, v174
	v_fmac_f32_e32 v14, v175, v175
	v_fmac_f32_e32 v14, v176, v176
	v_fmac_f32_e32 v14, v177, v177
	s_waitcnt vmcnt(14)
	v_pk_fma_f32 v[178:179], v[0:1], v[96:97], v[178:179]
	v_pk_fma_f32 v[180:181], v[2:3], v[98:99], v[180:181]
	global_store_dwordx4 v165, v[178:181], s[66:67] offset:576
	v_pk_mul_f32 v[0:1], v[178:179], v[196:197]
	v_pk_mul_f32 v[2:3], v[180:181], v[198:199]
	v_cvt_pk_bf16_f32 v0, v0, v1
	v_cvt_pk_bf16_f32 v1, v2, v3
	global_store_dwordx2 v173, v[0:1], s[8:9] offset:288
	v_fmac_f32_e32 v14, v178, v178
	v_fmac_f32_e32 v14, v179, v179
	v_fmac_f32_e32 v14, v180, v180
	v_fmac_f32_e32 v14, v181, v181
	ds_bpermute_b32 v143, v216, v142
	ds_bpermute_b32 v127, v216, v126
	ds_bpermute_b32 v111, v216, v110
	ds_bpermute_b32 v83, v216, v82
	ds_bpermute_b32 v63, v216, v62
	ds_bpermute_b32 v47, v216, v46
	ds_bpermute_b32 v31, v216, v30
	ds_bpermute_b32 v15, v216, v14
	s_waitcnt lgkmcnt(0)
	v_add_f32_e32 v142, v142, v143
	v_add_f32_e32 v126, v126, v127
	v_add_f32_e32 v110, v110, v111
	v_add_f32_e32 v82, v82, v83
	v_add_f32_e32 v62, v62, v63
	v_add_f32_e32 v46, v46, v47
	v_add_f32_e32 v30, v30, v31
	v_add_f32_e32 v14, v14, v15
	ds_bpermute_b32 v143, v217, v142
	ds_bpermute_b32 v127, v217, v126
	ds_bpermute_b32 v111, v217, v110
	ds_bpermute_b32 v83, v217, v82
	ds_bpermute_b32 v63, v217, v62
	ds_bpermute_b32 v47, v217, v46
	ds_bpermute_b32 v31, v217, v30
	ds_bpermute_b32 v15, v217, v14
	s_lshl_b32 s25, s34, 2
	s_or_b32 s25, s25, s47
	s_lshl_b32 s25, s25, 16
	v_lshl_add_u32 v164, s36, 8, v166
	v_lshl_add_u32 v164, v164, 2, s25
	s_waitcnt lgkmcnt(0)
	v_add_f32_e32 v142, v142, v143
	v_add_f32_e32 v126, v126, v127
	v_add_f32_e32 v110, v110, v111
	v_add_f32_e32 v82, v82, v83
	v_add_f32_e32 v62, v62, v63
	v_add_f32_e32 v46, v46, v47
	v_add_f32_e32 v30, v30, v31
	v_add_f32_e32 v14, v14, v15
	s_and_saveexec_b64 s[100:101], s[4:5]
	global_store_dword v164, v142, s[48:49]
	global_store_dword v164, v126, s[48:49] offset:64
	global_store_dword v164, v110, s[48:49] offset:128
	global_store_dword v164, v82, s[48:49] offset:192
	global_store_dword v164, v62, s[48:49] offset:512
	global_store_dword v164, v46, s[48:49] offset:576
	global_store_dword v164, v30, s[48:49] offset:640
	global_store_dword v164, v14, s[48:49] offset:704
	s_or_b64 exec, exec, s[100:101]
	s_andn2_b64 vcc, exec, s[6:7]
	s_mov_b64 s[6:7], -1
	s_cbranch_vccnz .LBB0_886
	s_andn2_b64 vcc, exec, s[10:11]
	s_cbranch_vccnz .LBB0_885
	s_branch .LBB0_885
.LBB0_916:
	s_waitcnt vmcnt(0)
	s_and_b64 vcc, exec, s[14:15]
	s_cbranch_vccz .Lnoalign_p5
	s_barrier

; __device__ __forceinline__ unsigned cvt_pk_bf16(float lo, float hi) { unsigned r; asm volatile("v_cvt_pk_bf16_f32 %0, %1, %2" : "=v"(r) : "v"(lo), "v"(hi)); return r; }
;     __device__ __forceinline__ void operator()(const f32x4 (&acc)[2][2][4][2], const Unit& u, int wr, int wc, int fr, int fq) const {
;         const int row0 = u.pm * BM + wr * 64 + fr, col0 = u.pn * BM + wc * 32 + 8 * fq, b = (u.pm * BM) >> 12;
;         f32x4 cbv[2][2];
; #pragma unroll
;         for (int bj = 0; bj < 2; ++bj)
; #pragma unroll
;             for (int n = 0; n < 2; ++n) cbv[bj][n] = *(const f32x4*)(cb + (size_t)b * 8192 + col0 + bj * HALF + 4 * n);
; #pragma unroll
;         for (int ai = 0; ai < 2; ++ai)
; #pragma unroll
;             for (int m = 0; m < 4; ++m) { const int rl = wr * 64 + fr + ai * HALF + m * 16; bf16_t* rowp = O + (size_t)(u.pm * BM + rl) * ldc + col0;
;                 const float rs = rstd[((u.pm >> 2) & 1) * 256 + rl];
; #pragma unroll
;                 for (int bj = 0; bj < 2; ++bj) { float v[8];
; #pragma unroll
;                     for (int e = 0; e < 8; ++e) { const float x = fmaxf(acc[ai][bj][m][e >> 2][e & 3] * rs + cbv[bj][e >> 2][e & 3], 0.f); v[e] = x * x; }
;                     u32x4 w; w.x = cvt_pk_bf16(v[0], v[1]); w.y = cvt_pk_bf16(v[2], v[3]); w.z = cvt_pk_bf16(v[4], v[5]); w.w = cvt_pk_bf16(v[6], v[7]);
;                     *(u32x4*)(rowp + bj * HALF) = w; } }
.LBB0_997:
	s_ashr_i32 s24, s22, 4
	s_ashr_i32 s25, s24, 31
	s_lshl_b64 s[24:25], s[24:25], 15
	v_lshl_or_b32 v160, s42, 8, v171
	s_add_u32 s24, s36, s24
	s_addc_u32 s25, s37, s25
	v_ashrrev_i32_e32 v161, 31, v160
	v_lshl_add_u64 v[128:129], v[160:161], 2, s[24:25]
	global_load_dwordx4 v[140:143], v[128:129], off
	global_load_dwordx4 v[136:139], v[128:129], off offset:16
	global_load_dwordx4 v[132:135], v[128:129], off offset:512
	s_nop 0
	global_load_dwordx4 v[128:131], v[128:129], off offset:528
	s_lshl_b32 s15, s22, 8
	s_and_b32 s17, s15, 0x400
	v_add_u32_e32 v176, s17, v172
	ds_read_b32 v177, v176
	v_add_u32_e32 v178, s15, v162
	v_ashrrev_i32_e32 v179, 31, v178
	v_lshlrev_b64 v[178:179], 14, v[178:179]
	v_lshlrev_b64 v[160:161], 1, v[160:161]
	v_lshl_add_u64 v[178:179], s[72:73], 0, v[178:179]
	v_lshl_add_u64 v[178:179], v[178:179], 0, v[160:161]
	v_add_u32_e32 v180, s15, v164
	v_ashrrev_i32_e32 v181, 31, v180
	s_andn2_b64 vcc, exec, s[4:5]
	s_mov_b64 s[4:5], -1
	s_waitcnt vmcnt(0) lgkmcnt(0)
	v_fma_f32 v124, v124, v177, v140
	v_fma_f32 v125, v125, v177, v141
	v_fma_f32 v126, v126, v177, v142
	v_fma_f32 v127, v127, v177, v143
	v_fma_f32 v120, v120, v177, v136
	v_fma_f32 v121, v121, v177, v137
	v_fma_f32 v122, v122, v177, v138
	v_fma_f32 v123, v123, v177, v139
	v_fma_f32 v118, v118, v177, v134
	v_fma_f32 v112, v112, v177, v128
	v_fma_f32 v113, v113, v177, v129
	v_fma_f32 v114, v114, v177, v130
	v_fma_f32 v115, v115, v177, v131
	v_fma_f32 v116, v116, v177, v132
	v_fma_f32 v117, v117, v177, v133
	v_fma_f32 v119, v119, v177, v135
	v_max_f32_e32 v124, 0, v124
	v_max_f32_e32 v125, 0, v125
	v_max_f32_e32 v126, 0, v126
	v_max_f32_e32 v127, 0, v127
	v_max_f32_e32 v120, 0, v120
	v_max_f32_e32 v121, 0, v121
	v_max_f32_e32 v122, 0, v122
	v_max_f32_e32 v123, 0, v123
	v_max_f32_e32 v118, 0, v118
	v_max_f32_e32 v112, 0, v112
	v_max_f32_e32 v113, 0, v113
	v_max_f32_e32 v114, 0, v114
	v_max_f32_e32 v115, 0, v115
	v_max_f32_e32 v116, 0, v116
	v_max_f32_e32 v117, 0, v117
	v_max_f32_e32 v119, 0, v119
	v_mul_f32_e32 v124, v124, v124
	v_mul_f32_e32 v125, v125, v125
	v_mul_f32_e32 v126, v126, v126
	v_mul_f32_e32 v127, v127, v127
	v_mul_f32_e32 v120, v120, v120
	v_mul_f32_e32 v121, v121, v121
	v_mul_f32_e32 v122, v122, v122
	v_mul_f32_e32 v123, v123, v123
	v_mul_f32_e32 v118, v118, v118
	v_mul_f32_e32 v177, v112, v112
	v_mul_f32_e32 v182, v113, v113
	v_mul_f32_e32 v183, v114, v114
	v_mul_f32_e32 v184, v115, v115
	v_cvt_pk_bf16_f32 v112, v124, v125
	v_cvt_pk_bf16_f32 v113, v126, v127
	v_cvt_pk_bf16_f32 v114, v120, v121
	v_cvt_pk_bf16_f32 v115, v122, v123
	v_mul_f32_e32 v116, v116, v116
	v_mul_f32_e32 v117, v117, v117
	v_mul_f32_e32 v119, v119, v119
	global_store_dwordx4 v[178:179], v[112:115], off
	s_nop 1
	v_cvt_pk_bf16_f32 v112, v116, v117
	v_cvt_pk_bf16_f32 v113, v118, v119
	v_cvt_pk_bf16_f32 v114, v177, v182
	v_cvt_pk_bf16_f32 v115, v183, v184
	ds_read_b32 v118, v176 offset:64
	global_store_dwordx4 v[178:179], v[112:115], off offset:256
	v_lshlrev_b64 v[116:117], 14, v[180:181]
	v_lshl_add_u64 v[116:117], s[72:73], 0, v[116:117]
	v_lshl_add_u64 v[116:117], v[116:117], 0, v[160:161]
	s_waitcnt lgkmcnt(0)
	v_fma_f32 v104, v104, v118, v136
	v_max_f32_e32 v104, 0, v104
	v_mul_f32_e32 v112, v104, v104
	v_fma_f32 v104, v105, v118, v137
	v_max_f32_e32 v104, 0, v104
	v_mul_f32_e32 v113, v104, v104
	v_fma_f32 v104, v106, v118, v138
	v_max_f32_e32 v104, 0, v104
	v_fma_f32 v108, v108, v118, v140
	v_fma_f32 v109, v109, v118, v141
	v_mul_f32_e32 v114, v104, v104
	v_fma_f32 v104, v107, v118, v139
	v_fma_f32 v110, v110, v118, v142
	v_fma_f32 v111, v111, v118, v143
	v_max_f32_e32 v108, 0, v108
	v_max_f32_e32 v109, 0, v109
	v_max_f32_e32 v104, 0, v104
	v_fma_f32 v96, v96, v118, v128
	v_max_f32_e32 v110, 0, v110
	v_max_f32_e32 v111, 0, v111
	v_mul_f32_e32 v108, v108, v108
	v_mul_f32_e32 v109, v109, v109
	v_mul_f32_e32 v107, v104, v104
	v_cvt_pk_bf16_f32 v104, v108, v109
	v_max_f32_e32 v96, 0, v96
	v_mul_f32_e32 v110, v110, v110
	v_mul_f32_e32 v111, v111, v111
	v_cvt_pk_bf16_f32 v105, v110, v111
	v_cvt_pk_bf16_f32 v106, v112, v113
	v_cvt_pk_bf16_f32 v107, v114, v107
	global_store_dwordx4 v[116:117], v[104:107], off
	v_fma_f32 v100, v100, v118, v132
	v_fma_f32 v101, v101, v118, v133
	v_mul_f32_e32 v104, v96, v96
	v_fma_f32 v96, v97, v118, v129
	v_max_f32_e32 v96, 0, v96
	v_mul_f32_e32 v105, v96, v96
	v_fma_f32 v96, v98, v118, v130
	v_max_f32_e32 v96, 0, v96
	v_fma_f32 v102, v102, v118, v134
	v_fma_f32 v103, v103, v118, v135
	v_mul_f32_e32 v106, v96, v96
	v_fma_f32 v96, v99, v118, v131
	v_max_f32_e32 v100, 0, v100
	v_max_f32_e32 v101, 0, v101
	v_max_f32_e32 v102, 0, v102
	v_max_f32_e32 v103, 0, v103
	v_max_f32_e32 v96, 0, v96
	v_mul_f32_e32 v100, v100, v100
	v_mul_f32_e32 v101, v101, v101
	v_mul_f32_e32 v102, v102, v102
	v_mul_f32_e32 v103, v103, v103
	v_mul_f32_e32 v99, v96, v96
	v_cvt_pk_bf16_f32 v96, v100, v101
	v_cvt_pk_bf16_f32 v97, v102, v103
	v_cvt_pk_bf16_f32 v98, v104, v105
	v_cvt_pk_bf16_f32 v99, v106, v99
	global_store_dwordx4 v[116:117], v[96:99], off offset:256
	ds_read_b32 v98, v176 offset:128
	s_waitcnt lgkmcnt(0)
; __device__ __forceinline__ unsigned cvt_pk_bf16(float lo, float hi) { unsigned r; asm volatile("v_cvt_pk_bf16_f32 %0, %1, %2" : "=v"(r) : "v"(lo), "v"(hi)); return r; }
;     __device__ __forceinline__ void operator()(const f32x4 (&acc)[2][2][4][2], const Unit& u, int wr, int wc, int fr, int fq) const {
;     ...
; #pragma unroll
;         for (int ai = 0; ai < 2; ++ai)
; #pragma unroll
;             for (int m = 0; m < 4; ++m) { const int rl = wr * 64 + fr + ai * HALF + m * 16; bf16_t* rowp = O + (size_t)(u.pm * BM + rl) * ldc + col0;
;                 const float rs = rstd[((u.pm >> 2) & 1) * 256 + rl];
; #pragma unroll
;                 for (int bj = 0; bj < 2; ++bj) { float v[8];
; #pragma unroll
;                     for (int e = 0; e < 8; ++e) { const float x = fmaxf(acc[ai][bj][m][e >> 2][e & 3] * rs + cbv[bj][e >> 2][e & 3], 0.f); v[e] = x * x; }
;                     u32x4 w; w.x = cvt_pk_bf16(v[0], v[1]); w.y = cvt_pk_bf16(v[2], v[3]); w.z = cvt_pk_bf16(v[4], v[5]); w.w = cvt_pk_bf16(v[6], v[7]);
;                     *(u32x4*)(rowp + bj * HALF) = w; } }
	v_fma_f32 v88, v88, v98, v136
	v_max_f32_e32 v88, 0, v88
	v_mul_f32_e32 v99, v88, v88
	v_fma_f32 v88, v89, v98, v137
	v_max_f32_e32 v88, 0, v88
	v_add_u32_e32 v96, s15, v165
	v_mul_f32_e32 v100, v88, v88
	v_fma_f32 v88, v90, v98, v138
	v_ashrrev_i32_e32 v97, 31, v96
	v_max_f32_e32 v88, 0, v88
	v_lshlrev_b64 v[96:97], 14, v[96:97]
	v_fma_f32 v92, v92, v98, v140
	v_fma_f32 v93, v93, v98, v141
	v_mul_f32_e32 v101, v88, v88
	v_fma_f32 v88, v91, v98, v139
	v_lshl_add_u64 v[96:97], s[72:73], 0, v[96:97]
	v_max_f32_e32 v92, 0, v92
	v_max_f32_e32 v93, 0, v93
	v_fma_f32 v94, v94, v98, v142
	v_fma_f32 v95, v95, v98, v143
	v_max_f32_e32 v88, 0, v88
	v_fma_f32 v80, v80, v98, v128
	v_lshl_add_u64 v[96:97], v[96:97], 0, v[160:161]
	v_mul_f32_e32 v92, v92, v92
	v_mul_f32_e32 v93, v93, v93
	v_max_f32_e32 v94, 0, v94
	v_max_f32_e32 v95, 0, v95
	v_mul_f32_e32 v91, v88, v88
	v_cvt_pk_bf16_f32 v88, v92, v93
	v_max_f32_e32 v80, 0, v80
	v_mul_f32_e32 v94, v94, v94
	v_mul_f32_e32 v95, v95, v95
	v_cvt_pk_bf16_f32 v89, v94, v95
	v_cvt_pk_bf16_f32 v90, v99, v100
	v_cvt_pk_bf16_f32 v91, v101, v91
	global_store_dwordx4 v[96:97], v[88:91], off
	v_fma_f32 v84, v84, v98, v132
	v_fma_f32 v85, v85, v98, v133
	v_mul_f32_e32 v88, v80, v80
	v_fma_f32 v80, v81, v98, v129
	v_max_f32_e32 v80, 0, v80
	v_mul_f32_e32 v89, v80, v80
	v_fma_f32 v80, v82, v98, v130
	v_max_f32_e32 v80, 0, v80
	v_fma_f32 v86, v86, v98, v134
	v_fma_f32 v87, v87, v98, v135
	v_mul_f32_e32 v90, v80, v80
	v_fma_f32 v80, v83, v98, v131
	v_max_f32_e32 v84, 0, v84
	v_max_f32_e32 v85, 0, v85
	v_max_f32_e32 v86, 0, v86
	v_max_f32_e32 v87, 0, v87
	v_max_f32_e32 v80, 0, v80
	v_mul_f32_e32 v84, v84, v84
	v_mul_f32_e32 v85, v85, v85
	v_mul_f32_e32 v86, v86, v86
	v_mul_f32_e32 v87, v87, v87
	v_mul_f32_e32 v83, v80, v80
	v_cvt_pk_bf16_f32 v80, v84, v85
	v_cvt_pk_bf16_f32 v81, v86, v87
	v_cvt_pk_bf16_f32 v82, v88, v89
	v_cvt_pk_bf16_f32 v83, v90, v83
	global_store_dwordx4 v[96:97], v[80:83], off offset:256
	ds_read_b32 v82, v176 offset:192
	s_waitcnt lgkmcnt(0)
	v_fma_f32 v72, v72, v82, v136
	v_max_f32_e32 v72, 0, v72
	v_mul_f32_e32 v83, v72, v72
	v_fma_f32 v72, v73, v82, v137
	v_max_f32_e32 v72, 0, v72
	v_add_u32_e32 v80, s15, v166
	v_mul_f32_e32 v84, v72, v72
	v_fma_f32 v72, v74, v82, v138
	v_ashrrev_i32_e32 v81, 31, v80
	v_max_f32_e32 v72, 0, v72
	v_lshlrev_b64 v[80:81], 14, v[80:81]
	v_fma_f32 v76, v76, v82, v140
	v_fma_f32 v77, v77, v82, v141
	v_mul_f32_e32 v85, v72, v72
	v_fma_f32 v72, v75, v82, v139
	v_lshl_add_u64 v[80:81], s[72:73], 0, v[80:81]
	v_max_f32_e32 v76, 0, v76
	v_max_f32_e32 v77, 0, v77
	v_fma_f32 v78, v78, v82, v142
	v_fma_f32 v79, v79, v82, v143
	v_max_f32_e32 v72, 0, v72
	v_fma_f32 v64, v64, v82, v128
	v_lshl_add_u64 v[80:81], v[80:81], 0, v[160:161]
	v_mul_f32_e32 v76, v76, v76
	v_mul_f32_e32 v77, v77, v77
	v_max_f32_e32 v78, 0, v78
	v_max_f32_e32 v79, 0, v79
	v_mul_f32_e32 v75, v72, v72
	v_cvt_pk_bf16_f32 v72, v76, v77
	v_max_f32_e32 v64, 0, v64
	v_mul_f32_e32 v78, v78, v78
	v_mul_f32_e32 v79, v79, v79
	v_cvt_pk_bf16_f32 v73, v78, v79
	v_cvt_pk_bf16_f32 v74, v83, v84
	v_cvt_pk_bf16_f32 v75, v85, v75
	global_store_dwordx4 v[80:81], v[72:75], off
	v_fma_f32 v68, v68, v82, v132
	v_fma_f32 v69, v69, v82, v133
	v_mul_f32_e32 v72, v64, v64
	v_fma_f32 v64, v65, v82, v129
	v_max_f32_e32 v64, 0, v64
	v_mul_f32_e32 v73, v64, v64
	v_fma_f32 v64, v66, v82, v130
	v_max_f32_e32 v64, 0, v64
	v_fma_f32 v70, v70, v82, v134
	v_fma_f32 v71, v71, v82, v135
	v_mul_f32_e32 v74, v64, v64
	v_fma_f32 v64, v67, v82, v131
	v_max_f32_e32 v68, 0, v68
	v_max_f32_e32 v69, 0, v69
	v_max_f32_e32 v70, 0, v70
	v_max_f32_e32 v71, 0, v71
	v_max_f32_e32 v64, 0, v64
	v_mul_f32_e32 v68, v68, v68
	v_mul_f32_e32 v69, v69, v69
	v_mul_f32_e32 v70, v70, v70
	v_mul_f32_e32 v71, v71, v71
	v_mul_f32_e32 v67, v64, v64
	v_cvt_pk_bf16_f32 v64, v68, v69
	v_cvt_pk_bf16_f32 v65, v70, v71
	v_cvt_pk_bf16_f32 v66, v72, v73
	v_cvt_pk_bf16_f32 v67, v74, v67
	global_store_dwordx4 v[80:81], v[64:67], off offset:256
	ds_read_b32 v66, v176 offset:512
	s_waitcnt lgkmcnt(0)
	v_fma_f32 v56, v56, v66, v136
	v_max_f32_e32 v56, 0, v56
	v_mul_f32_e32 v67, v56, v56
	v_fma_f32 v56, v57, v66, v137
	v_max_f32_e32 v56, 0, v56
	v_add_u32_e32 v64, s15, v167
	v_mul_f32_e32 v68, v56, v56
	v_fma_f32 v56, v58, v66, v138
	v_ashrrev_i32_e32 v65, 31, v64
	v_max_f32_e32 v56, 0, v56
	v_lshlrev_b64 v[64:65], 14, v[64:65]
	v_fma_f32 v60, v60, v66, v140
	v_fma_f32 v61, v61, v66, v141
	v_mul_f32_e32 v69, v56, v56
	v_fma_f32 v56, v59, v66, v139
	v_lshl_add_u64 v[64:65], s[72:73], 0, v[64:65]
	v_max_f32_e32 v60, 0, v60
	v_max_f32_e32 v61, 0, v61
	v_fma_f32 v62, v62, v66, v142
	v_fma_f32 v63, v63, v66, v143
	v_max_f32_e32 v56, 0, v56
	v_fma_f32 v48, v48, v66, v128
	v_lshl_add_u64 v[64:65], v[64:65], 0, v[160:161]
	v_mul_f32_e32 v60, v60, v60
	v_mul_f32_e32 v61, v61, v61
	v_max_f32_e32 v62, 0, v62
	v_max_f32_e32 v63, 0, v63
	v_mul_f32_e32 v59, v56, v56
	v_cvt_pk_bf16_f32 v56, v60, v61
	v_max_f32_e32 v48, 0, v48
	v_mul_f32_e32 v62, v62, v62
	v_mul_f32_e32 v63, v63, v63
	v_cvt_pk_bf16_f32 v57, v62, v63
	v_cvt_pk_bf16_f32 v58, v67, v68
	v_cvt_pk_bf16_f32 v59, v69, v59
	global_store_dwordx4 v[64:65], v[56:59], off
	v_fma_f32 v52, v52, v66, v132
	v_fma_f32 v53, v53, v66, v133
	v_mul_f32_e32 v56, v48, v48
	v_fma_f32 v48, v49, v66, v129
	v_max_f32_e32 v48, 0, v48
	v_mul_f32_e32 v57, v48, v48
	v_fma_f32 v48, v50, v66, v130
	v_max_f32_e32 v48, 0, v48
	v_fma_f32 v54, v54, v66, v134
	v_fma_f32 v55, v55, v66, v135
	v_mul_f32_e32 v58, v48, v48
	v_fma_f32 v48, v51, v66, v131
	v_max_f32_e32 v52, 0, v52
	v_max_f32_e32 v53, 0, v53
	v_max_f32_e32 v54, 0, v54
	v_max_f32_e32 v55, 0, v55
	v_max_f32_e32 v48, 0, v48
	v_mul_f32_e32 v52, v52, v52
	v_mul_f32_e32 v53, v53, v53
	v_mul_f32_e32 v54, v54, v54
	v_mul_f32_e32 v55, v55, v55
	v_mul_f32_e32 v51, v48, v48
	v_cvt_pk_bf16_f32 v48, v52, v53
	v_cvt_pk_bf16_f32 v49, v54, v55
	v_cvt_pk_bf16_f32 v50, v56, v57
	v_cvt_pk_bf16_f32 v51, v58, v51
	global_store_dwordx4 v[64:65], v[48:51], off offset:256
	ds_read_b32 v50, v176 offset:576
	s_waitcnt lgkmcnt(0)
; __device__ __forceinline__ unsigned cvt_pk_bf16(float lo, float hi) { unsigned r; asm volatile("v_cvt_pk_bf16_f32 %0, %1, %2" : "=v"(r) : "v"(lo), "v"(hi)); return r; }
; #define PG8_WAIT_V(n) asm volatile("s_waitcnt vmcnt(" #n ")" ::: "memory")
; #define PG8_BAR __builtin_amdgcn_s_barrier()
;     __device__ __forceinline__ void operator()(const f32x4 (&acc)[2][2][4][2], const Unit& u, int wr, int wc, int fr, int fq) const {
;     ...
;             for (int m = 0; m < 4; ++m) { const int rl = wr * 64 + fr + ai * HALF + m * 16; bf16_t* rowp = O + (size_t)(u.pm * BM + rl) * ldc + col0;
;                 const float rs = rstd[((u.pm >> 2) & 1) * 256 + rl];
; #pragma unroll
;                 for (int bj = 0; bj < 2; ++bj) { float v[8];
; #pragma unroll
;                     for (int e = 0; e < 8; ++e) { const float x = fmaxf(acc[ai][bj][m][e >> 2][e & 3] * rs + cbv[bj][e >> 2][e & 3], 0.f); v[e] = x * x; }
;                     u32x4 w; w.x = cvt_pk_bf16(v[0], v[1]); w.y = cvt_pk_bf16(v[2], v[3]); w.z = cvt_pk_bf16(v[4], v[5]); w.w = cvt_pk_bf16(v[6], v[7]);
;                     *(u32x4*)(rowp + bj * HALF) = w; } }
; template <class Epi, class Sched, bool ALIGN_EPI = false, bool SP2 = false>
; __device__ __forceinline__ void gemm_phase(PG8_LAS unsigned char* lds, const Gemm g, const Sched& S, const Epi& E) {
;     ...
;         cur = nxt; cA = nA; cB = nB; ++ui;
;         if constexpr (ALIGN_EPI) { if (wr == 1) PG8_BAR; }
;     }
;     PG8_WAIT_V(0);
;     if constexpr (!ALIGN_EPI) { if (wr == 0) PG8_BAR; }
	v_fma_f32 v40, v40, v50, v136
	v_max_f32_e32 v40, 0, v40
	v_mul_f32_e32 v51, v40, v40
	v_fma_f32 v40, v41, v50, v137
	v_max_f32_e32 v40, 0, v40
	v_add_u32_e32 v48, s15, v168
	v_mul_f32_e32 v52, v40, v40
	v_fma_f32 v40, v42, v50, v138
	v_ashrrev_i32_e32 v49, 31, v48
	v_max_f32_e32 v40, 0, v40
	v_lshlrev_b64 v[48:49], 14, v[48:49]
	v_fma_f32 v44, v44, v50, v140
	v_fma_f32 v45, v45, v50, v141
	v_mul_f32_e32 v53, v40, v40
	v_fma_f32 v40, v43, v50, v139
	v_lshl_add_u64 v[48:49], s[72:73], 0, v[48:49]
	v_max_f32_e32 v44, 0, v44
	v_max_f32_e32 v45, 0, v45
	v_fma_f32 v46, v46, v50, v142
	v_fma_f32 v47, v47, v50, v143
	v_max_f32_e32 v40, 0, v40
	v_fma_f32 v32, v32, v50, v128
	v_lshl_add_u64 v[48:49], v[48:49], 0, v[160:161]
	v_mul_f32_e32 v44, v44, v44
	v_mul_f32_e32 v45, v45, v45
	v_max_f32_e32 v46, 0, v46
	v_max_f32_e32 v47, 0, v47
	v_mul_f32_e32 v43, v40, v40
	v_cvt_pk_bf16_f32 v40, v44, v45
	v_max_f32_e32 v32, 0, v32
	v_mul_f32_e32 v46, v46, v46
	v_mul_f32_e32 v47, v47, v47
	v_cvt_pk_bf16_f32 v41, v46, v47
	v_cvt_pk_bf16_f32 v42, v51, v52
	v_cvt_pk_bf16_f32 v43, v53, v43
	global_store_dwordx4 v[48:49], v[40:43], off
	v_fma_f32 v36, v36, v50, v132
	v_fma_f32 v37, v37, v50, v133
	v_mul_f32_e32 v40, v32, v32
	v_fma_f32 v32, v33, v50, v129
	v_max_f32_e32 v32, 0, v32
	v_mul_f32_e32 v41, v32, v32
	v_fma_f32 v32, v34, v50, v130
	v_max_f32_e32 v32, 0, v32
	v_fma_f32 v38, v38, v50, v134
	v_fma_f32 v39, v39, v50, v135
	v_mul_f32_e32 v42, v32, v32
	v_fma_f32 v32, v35, v50, v131
	v_max_f32_e32 v36, 0, v36
	v_max_f32_e32 v37, 0, v37
	v_max_f32_e32 v38, 0, v38
	v_max_f32_e32 v39, 0, v39
	v_max_f32_e32 v32, 0, v32
	v_mul_f32_e32 v36, v36, v36
	v_mul_f32_e32 v37, v37, v37
	v_mul_f32_e32 v38, v38, v38
	v_mul_f32_e32 v39, v39, v39
	v_mul_f32_e32 v35, v32, v32
	v_cvt_pk_bf16_f32 v32, v36, v37
	v_cvt_pk_bf16_f32 v33, v38, v39
	v_cvt_pk_bf16_f32 v34, v40, v41
	v_cvt_pk_bf16_f32 v35, v42, v35
	global_store_dwordx4 v[48:49], v[32:35], off offset:256
	ds_read_b32 v34, v176 offset:640
	s_waitcnt lgkmcnt(0)
	v_fma_f32 v24, v24, v34, v136
	v_max_f32_e32 v24, 0, v24
	v_mul_f32_e32 v35, v24, v24
	v_fma_f32 v24, v25, v34, v137
	v_max_f32_e32 v24, 0, v24
	v_add_u32_e32 v32, s15, v169
	v_mul_f32_e32 v36, v24, v24
	v_fma_f32 v24, v26, v34, v138
	v_ashrrev_i32_e32 v33, 31, v32
	v_max_f32_e32 v24, 0, v24
	v_lshlrev_b64 v[32:33], 14, v[32:33]
	v_fma_f32 v28, v28, v34, v140
	v_fma_f32 v29, v29, v34, v141
	v_mul_f32_e32 v37, v24, v24
	v_fma_f32 v24, v27, v34, v139
	v_lshl_add_u64 v[32:33], s[72:73], 0, v[32:33]
	v_max_f32_e32 v28, 0, v28
	v_max_f32_e32 v29, 0, v29
	v_fma_f32 v30, v30, v34, v142
	v_fma_f32 v31, v31, v34, v143
	v_max_f32_e32 v24, 0, v24
	v_fma_f32 v16, v16, v34, v128
	v_lshl_add_u64 v[32:33], v[32:33], 0, v[160:161]
	v_mul_f32_e32 v28, v28, v28
	v_mul_f32_e32 v29, v29, v29
	v_max_f32_e32 v30, 0, v30
	v_max_f32_e32 v31, 0, v31
	v_mul_f32_e32 v27, v24, v24
	v_cvt_pk_bf16_f32 v24, v28, v29
	v_max_f32_e32 v16, 0, v16
	v_mul_f32_e32 v30, v30, v30
	v_mul_f32_e32 v31, v31, v31
	v_cvt_pk_bf16_f32 v25, v30, v31
	v_cvt_pk_bf16_f32 v26, v35, v36
	v_cvt_pk_bf16_f32 v27, v37, v27
	global_store_dwordx4 v[32:33], v[24:27], off
	v_fma_f32 v20, v20, v34, v132
	v_fma_f32 v21, v21, v34, v133
	v_mul_f32_e32 v24, v16, v16
	v_fma_f32 v16, v17, v34, v129
	v_max_f32_e32 v16, 0, v16
	v_mul_f32_e32 v25, v16, v16
	v_fma_f32 v16, v18, v34, v130
	v_max_f32_e32 v16, 0, v16
	v_fma_f32 v22, v22, v34, v134
	v_fma_f32 v23, v23, v34, v135
	v_mul_f32_e32 v26, v16, v16
	v_fma_f32 v16, v19, v34, v131
	v_max_f32_e32 v20, 0, v20
	v_max_f32_e32 v21, 0, v21
	v_max_f32_e32 v22, 0, v22
	v_max_f32_e32 v23, 0, v23
	v_max_f32_e32 v16, 0, v16
	v_mul_f32_e32 v20, v20, v20
	v_mul_f32_e32 v21, v21, v21
	v_mul_f32_e32 v22, v22, v22
	v_mul_f32_e32 v23, v23, v23
	v_mul_f32_e32 v19, v16, v16
	v_cvt_pk_bf16_f32 v16, v20, v21
	v_cvt_pk_bf16_f32 v17, v22, v23
	v_cvt_pk_bf16_f32 v18, v24, v25
	v_cvt_pk_bf16_f32 v19, v26, v19
	global_store_dwordx4 v[32:33], v[16:19], off offset:256
	ds_read_b32 v18, v176 offset:704
	s_waitcnt lgkmcnt(0)
	v_fma_f32 v8, v8, v18, v136
	v_max_f32_e32 v8, 0, v8
	v_mul_f32_e32 v19, v8, v8
	v_fma_f32 v8, v9, v18, v137
	v_add_u32_e32 v16, s15, v170
	v_max_f32_e32 v8, 0, v8
	v_ashrrev_i32_e32 v17, 31, v16
	v_mul_f32_e32 v20, v8, v8
	v_fma_f32 v8, v10, v18, v138
	v_lshlrev_b64 v[16:17], 14, v[16:17]
	v_fma_f32 v12, v12, v18, v140
	v_fma_f32 v13, v13, v18, v141
	v_max_f32_e32 v8, 0, v8
	v_fmac_f32_e32 v139, v11, v18
	v_lshl_add_u64 v[16:17], s[72:73], 0, v[16:17]
	v_max_f32_e32 v12, 0, v12
	v_max_f32_e32 v13, 0, v13
	v_fma_f32 v14, v14, v18, v142
	v_fmac_f32_e32 v143, v15, v18
	v_mul_f32_e32 v21, v8, v8
	v_max_f32_e32 v8, 0, v139
	v_fma_f32 v0, v0, v18, v128
	v_lshl_add_u64 v[16:17], v[16:17], 0, v[160:161]
	v_mul_f32_e32 v12, v12, v12
	v_mul_f32_e32 v13, v13, v13
	v_max_f32_e32 v14, 0, v14
	v_max_f32_e32 v15, 0, v143
	v_mul_f32_e32 v11, v8, v8
	v_cvt_pk_bf16_f32 v8, v12, v13
	v_max_f32_e32 v0, 0, v0
	v_mul_f32_e32 v14, v14, v14
	v_mul_f32_e32 v15, v15, v15
	v_cvt_pk_bf16_f32 v9, v14, v15
	v_cvt_pk_bf16_f32 v10, v19, v20
	v_cvt_pk_bf16_f32 v11, v21, v11
	global_store_dwordx4 v[16:17], v[8:11], off
	v_fmac_f32_e32 v131, v3, v18
	v_fma_f32 v4, v4, v18, v132
	v_mul_f32_e32 v8, v0, v0
	v_fma_f32 v0, v1, v18, v129
	v_max_f32_e32 v0, 0, v0
	v_mul_f32_e32 v9, v0, v0
	v_fma_f32 v0, v2, v18, v130
	v_max_f32_e32 v0, 0, v0
	v_fma_f32 v5, v5, v18, v133
	v_fma_f32 v6, v6, v18, v134
	v_fmac_f32_e32 v135, v7, v18
	v_mul_f32_e32 v10, v0, v0
	v_max_f32_e32 v0, 0, v131
	v_max_f32_e32 v4, 0, v4
	v_max_f32_e32 v5, 0, v5
	v_max_f32_e32 v6, 0, v6
	v_max_f32_e32 v7, 0, v135
	v_mul_f32_e32 v3, v0, v0
	v_mul_f32_e32 v4, v4, v4
	v_mul_f32_e32 v5, v5, v5
	v_mul_f32_e32 v6, v6, v6
	v_mul_f32_e32 v7, v7, v7
	v_cvt_pk_bf16_f32 v0, v4, v5
	v_cvt_pk_bf16_f32 v1, v6, v7
	v_cvt_pk_bf16_f32 v2, v8, v9
	v_cvt_pk_bf16_f32 v3, v10, v3
	global_store_dwordx4 v[16:17], v[0:3], off offset:256
	s_cbranch_vccnz .LBB0_986
	s_andn2_b64 vcc, exec, s[6:7]
	s_cbranch_vccnz .LBB0_985
	s_branch .LBB0_985
.LBB0_1000:
	s_waitcnt vmcnt(0)
	s_and_b64 vcc, exec, s[12:13]
	s_cbranch_vccz .Lnoalign_p7
	s_barrier

;     __device__ __forceinline__ void operator()(const f32x4 (&acc)[2][2][4][2], const Unit& u, int wr, int wc, int fr, int fq) const {
;         const int row0 = u.pm * BM + wr * 64 + fr, col0 = u.pn * BM + wc * 32 + 4 * fq, b = (u.pm * BM) >> 12;
;         f32x4 gv[2][2];
; #pragma unroll
;         for (int bj = 0; bj < 2; ++bj)
; #pragma unroll
;             for (int n = 0; n < 2; ++n) gv[bj][n] = *(const f32x4*)(gate + (size_t)b * 12288 + col0 + bj * HALF + n * 16);
; #pragma unroll
;         for (int ai = 0; ai < 2; ++ai)
; #pragma unroll
;             for (int m = 0; m < 4; ++m) { const size_t off = (size_t)(row0 + ai * HALF + m * 16) * 2048 + col0;
; #pragma unroll
;                 for (int bj = 0; bj < 2; ++bj)
; #pragma unroll
;                     for (int n = 0; n < 2; ++n) { const f32x4 bs = __builtin_nontemporal_load((const f32x4*)(base + off + bj * HALF + n * 16));
;                         *(f32x4*)(out + off + bj * HALF + n * 16) = bs + gv[bj][n] * acc[ai][bj][m][n]; } }
.LBB0_1074:
	s_ashr_i32 s17, s24, 4
	v_lshl_add_u32 v160, s24, 8, v162
	v_lshl_or_b32 v64, s25, 8, v164
	s_mul_hi_i32 s19, s17, 0xc000
	s_mul_i32 s17, s17, 0xc000
	v_ashrrev_i32_e32 v161, 31, v160
	s_add_u32 s26, s40, s17
	v_ashrrev_i32_e32 v65, 31, v64
	v_lshlrev_b64 v[156:157], 13, v[160:161]
	s_addc_u32 s27, s41, s19
	v_lshlrev_b64 v[158:159], 2, v[64:65]
	v_lshl_add_u64 v[156:157], s[66:67], 0, v[156:157]
	v_lshl_add_u64 v[64:65], s[26:27], 0, v[158:159]
	v_lshl_add_u64 v[156:157], v[156:157], 0, v[158:159]
	global_load_dwordx4 v[128:131], v[64:65], off
	global_load_dwordx4 v[116:119], v[64:65], off offset:64
	global_load_dwordx4 v[108:111], v[64:65], off offset:512
	s_nop 0
	global_load_dwordx4 v[64:67], v[64:65], off offset:576
	s_mov_b64 s[24:25], -1
	s_mov_b64 s[98:99], 0x20000
	s_mov_b64 s[100:101], 0xa0000
	v_mov_b64_e32 v[158:159], v[156:157]
	global_load_dwordx4 v[168:171], v[158:159], off nt
	global_load_dwordx4 v[172:175], v[158:159], off offset:64 nt
	global_load_dwordx4 v[176:179], v[158:159], off offset:512 nt
	global_load_dwordx4 v[180:183], v[158:159], off offset:576 nt
	v_lshl_add_u64 v[158:159], v[158:159], 0, s[98:99]
	global_load_dwordx4 v[184:187], v[158:159], off nt
	global_load_dwordx4 v[188:191], v[158:159], off offset:64 nt
	global_load_dwordx4 v[192:195], v[158:159], off offset:512 nt
	global_load_dwordx4 v[196:199], v[158:159], off offset:576 nt
	v_lshl_add_u64 v[158:159], v[158:159], 0, s[98:99]
	global_load_dwordx4 v[200:203], v[158:159], off nt
	global_load_dwordx4 v[204:207], v[158:159], off offset:64 nt
	global_load_dwordx4 v[208:211], v[158:159], off offset:512 nt
	s_waitcnt vmcnt(10)
	v_pk_fma_f32 v[142:143], v[142:143], v[130:131], v[170:171]
	v_pk_fma_f32 v[140:141], v[140:141], v[128:129], v[168:169]
	global_store_dwordx4 v[156:157], v[140:143], off
	global_load_dwordx4 v[168:171], v[158:159], off offset:576 nt
	v_lshl_add_u64 v[158:159], v[158:159], 0, s[98:99]
	s_waitcnt vmcnt(11)
	v_pk_fma_f32 v[138:139], v[138:139], v[118:119], v[174:175]
	v_pk_fma_f32 v[136:137], v[136:137], v[116:117], v[172:173]
	global_store_dwordx4 v[156:157], v[136:139], off offset:64
	global_load_dwordx4 v[172:175], v[158:159], off nt
	s_waitcnt vmcnt(12)
	v_pk_fma_f32 v[134:135], v[134:135], v[110:111], v[178:179]
	v_pk_fma_f32 v[132:133], v[132:133], v[108:109], v[176:177]
	global_store_dwordx4 v[156:157], v[132:135], off offset:512
	global_load_dwordx4 v[176:179], v[158:159], off offset:64 nt
	s_waitcnt vmcnt(13)
	v_pk_fma_f32 v[126:127], v[126:127], v[66:67], v[182:183]
	v_pk_fma_f32 v[124:125], v[124:125], v[64:65], v[180:181]
	global_store_dwordx4 v[156:157], v[124:127], off offset:576
	v_lshl_add_u64 v[156:157], v[156:157], 0, s[98:99]
	global_load_dwordx4 v[180:183], v[158:159], off offset:512 nt
	s_waitcnt vmcnt(14)
	v_pk_fma_f32 v[122:123], v[122:123], v[130:131], v[186:187]
	v_pk_fma_f32 v[120:121], v[120:121], v[128:129], v[184:185]
	global_store_dwordx4 v[156:157], v[120:123], off
	global_load_dwordx4 v[184:187], v[158:159], off offset:576 nt
	v_lshl_add_u64 v[158:159], v[158:159], 0, s[100:101]
	s_waitcnt vmcnt(15)
	v_pk_fma_f32 v[114:115], v[114:115], v[118:119], v[190:191]
	v_pk_fma_f32 v[112:113], v[112:113], v[116:117], v[188:189]
	global_store_dwordx4 v[156:157], v[112:115], off offset:64
	global_load_dwordx4 v[188:191], v[158:159], off nt
	s_waitcnt vmcnt(16)
	v_pk_fma_f32 v[106:107], v[106:107], v[110:111], v[194:195]
	v_pk_fma_f32 v[104:105], v[104:105], v[108:109], v[192:193]
	global_store_dwordx4 v[156:157], v[104:107], off offset:512
	global_load_dwordx4 v[192:195], v[158:159], off offset:64 nt
	s_waitcnt vmcnt(17)
	v_pk_fma_f32 v[102:103], v[102:103], v[66:67], v[198:199]
	v_pk_fma_f32 v[100:101], v[100:101], v[64:65], v[196:197]
	global_store_dwordx4 v[156:157], v[100:103], off offset:576
	v_lshl_add_u64 v[156:157], v[156:157], 0, s[98:99]
	global_load_dwordx4 v[196:199], v[158:159], off offset:512 nt
	s_waitcnt vmcnt(18)
	v_pk_fma_f32 v[98:99], v[98:99], v[130:131], v[202:203]
	v_pk_fma_f32 v[96:97], v[96:97], v[128:129], v[200:201]
	global_store_dwordx4 v[156:157], v[96:99], off
	global_load_dwordx4 v[200:203], v[158:159], off offset:576 nt
	v_lshl_add_u64 v[158:159], v[158:159], 0, s[98:99]
	s_waitcnt vmcnt(19)
	v_pk_fma_f32 v[94:95], v[94:95], v[118:119], v[206:207]
	v_pk_fma_f32 v[92:93], v[92:93], v[116:117], v[204:205]
	global_store_dwordx4 v[156:157], v[92:95], off offset:64
	global_load_dwordx4 v[204:207], v[158:159], off nt
	s_waitcnt vmcnt(20)
	v_pk_fma_f32 v[90:91], v[90:91], v[110:111], v[210:211]
	v_pk_fma_f32 v[88:89], v[88:89], v[108:109], v[208:209]
	global_store_dwordx4 v[156:157], v[88:91], off offset:512
	global_load_dwordx4 v[208:211], v[158:159], off offset:64 nt
	s_waitcnt vmcnt(20)
	v_pk_fma_f32 v[86:87], v[86:87], v[66:67], v[170:171]
	v_pk_fma_f32 v[84:85], v[84:85], v[64:65], v[168:169]
	global_store_dwordx4 v[156:157], v[84:87], off offset:576
	v_lshl_add_u64 v[156:157], v[156:157], 0, s[98:99]
	global_load_dwordx4 v[168:171], v[158:159], off offset:512 nt
	s_waitcnt vmcnt(20)
; #define PG8_WAIT_V(n) asm volatile("s_waitcnt vmcnt(" #n ")" ::: "memory")
; #define PG8_BAR __builtin_amdgcn_s_barrier()
;     __device__ __forceinline__ void operator()(const f32x4 (&acc)[2][2][4][2], const Unit& u, int wr, int wc, int fr, int fq) const {
;     ...
;         for (int ai = 0; ai < 2; ++ai)
; #pragma unroll
;             for (int m = 0; m < 4; ++m) { const size_t off = (size_t)(row0 + ai * HALF + m * 16) * 2048 + col0;
; #pragma unroll
;                 for (int bj = 0; bj < 2; ++bj)
; #pragma unroll
;                     for (int n = 0; n < 2; ++n) { const f32x4 bs = __builtin_nontemporal_load((const f32x4*)(base + off + bj * HALF + n * 16));
;                         *(f32x4*)(out + off + bj * HALF + n * 16) = bs + gv[bj][n] * acc[ai][bj][m][n]; } }
; template <class Epi, class Sched, bool ALIGN_EPI = false, bool SP2 = false>
; __device__ __forceinline__ void gemm_phase(PG8_LAS unsigned char* lds, const Gemm g, const Sched& S, const Epi& E) {
;     ...
;         cur = nxt; cA = nA; cB = nB; ++ui;
;         if constexpr (ALIGN_EPI) { if (wr == 1) PG8_BAR; }
;     }
;     PG8_WAIT_V(0);
;     if constexpr (!ALIGN_EPI) { if (wr == 0) PG8_BAR; }
	v_pk_fma_f32 v[82:83], v[82:83], v[130:131], v[174:175]
	v_pk_fma_f32 v[80:81], v[80:81], v[128:129], v[172:173]
	global_store_dwordx4 v[156:157], v[80:83], off
	global_load_dwordx4 v[172:175], v[158:159], off offset:576 nt
	v_lshl_add_u64 v[158:159], v[158:159], 0, s[98:99]
	s_waitcnt vmcnt(20)
	v_pk_fma_f32 v[78:79], v[78:79], v[118:119], v[178:179]
	v_pk_fma_f32 v[76:77], v[76:77], v[116:117], v[176:177]
	global_store_dwordx4 v[156:157], v[76:79], off offset:64
	global_load_dwordx4 v[176:179], v[158:159], off nt
	s_waitcnt vmcnt(20)
	v_pk_fma_f32 v[74:75], v[74:75], v[110:111], v[182:183]
	v_pk_fma_f32 v[72:73], v[72:73], v[108:109], v[180:181]
	global_store_dwordx4 v[156:157], v[72:75], off offset:512
	global_load_dwordx4 v[180:183], v[158:159], off offset:64 nt
	s_waitcnt vmcnt(20)
	v_pk_fma_f32 v[70:71], v[70:71], v[66:67], v[186:187]
	v_pk_fma_f32 v[68:69], v[68:69], v[64:65], v[184:185]
	global_store_dwordx4 v[156:157], v[68:71], off offset:576
	v_lshl_add_u64 v[156:157], v[156:157], 0, s[100:101]
	global_load_dwordx4 v[184:187], v[158:159], off offset:512 nt
	s_waitcnt vmcnt(20)
	v_pk_fma_f32 v[62:63], v[62:63], v[130:131], v[190:191]
	v_pk_fma_f32 v[60:61], v[60:61], v[128:129], v[188:189]
	global_store_dwordx4 v[156:157], v[60:63], off
	global_load_dwordx4 v[188:191], v[158:159], off offset:576 nt
	v_lshl_add_u64 v[158:159], v[158:159], 0, s[98:99]
	s_waitcnt vmcnt(20)
	v_pk_fma_f32 v[58:59], v[58:59], v[118:119], v[194:195]
	v_pk_fma_f32 v[56:57], v[56:57], v[116:117], v[192:193]
	global_store_dwordx4 v[156:157], v[56:59], off offset:64
	global_load_dwordx4 v[192:195], v[158:159], off nt
	s_waitcnt vmcnt(20)
	v_pk_fma_f32 v[54:55], v[54:55], v[110:111], v[198:199]
	v_pk_fma_f32 v[52:53], v[52:53], v[108:109], v[196:197]
	global_store_dwordx4 v[156:157], v[52:55], off offset:512
	global_load_dwordx4 v[196:199], v[158:159], off offset:64 nt
	s_waitcnt vmcnt(20)
	v_pk_fma_f32 v[50:51], v[50:51], v[66:67], v[202:203]
	v_pk_fma_f32 v[48:49], v[48:49], v[64:65], v[200:201]
	global_store_dwordx4 v[156:157], v[48:51], off offset:576
	v_lshl_add_u64 v[156:157], v[156:157], 0, s[98:99]
	global_load_dwordx4 v[200:203], v[158:159], off offset:512 nt
	s_waitcnt vmcnt(20)
	v_pk_fma_f32 v[46:47], v[46:47], v[130:131], v[206:207]
	v_pk_fma_f32 v[44:45], v[44:45], v[128:129], v[204:205]
	global_store_dwordx4 v[156:157], v[44:47], off
	global_load_dwordx4 v[204:207], v[158:159], off offset:576 nt
	s_waitcnt vmcnt(20)
	v_pk_fma_f32 v[42:43], v[42:43], v[118:119], v[210:211]
	v_pk_fma_f32 v[40:41], v[40:41], v[116:117], v[208:209]
	global_store_dwordx4 v[156:157], v[40:43], off offset:64
	s_waitcnt vmcnt(19)
	v_pk_fma_f32 v[38:39], v[38:39], v[110:111], v[170:171]
	v_pk_fma_f32 v[36:37], v[36:37], v[108:109], v[168:169]
	global_store_dwordx4 v[156:157], v[36:39], off offset:512
	s_waitcnt vmcnt(18)
	v_pk_fma_f32 v[34:35], v[34:35], v[66:67], v[174:175]
	v_pk_fma_f32 v[32:33], v[32:33], v[64:65], v[172:173]
	global_store_dwordx4 v[156:157], v[32:35], off offset:576
	v_lshl_add_u64 v[156:157], v[156:157], 0, s[98:99]
	s_waitcnt vmcnt(17)
	v_pk_fma_f32 v[30:31], v[30:31], v[130:131], v[178:179]
	v_pk_fma_f32 v[28:29], v[28:29], v[128:129], v[176:177]
	global_store_dwordx4 v[156:157], v[28:31], off
	s_waitcnt vmcnt(16)
	v_pk_fma_f32 v[26:27], v[26:27], v[118:119], v[182:183]
	v_pk_fma_f32 v[24:25], v[24:25], v[116:117], v[180:181]
	global_store_dwordx4 v[156:157], v[24:27], off offset:64
	s_waitcnt vmcnt(15)
	v_pk_fma_f32 v[22:23], v[22:23], v[110:111], v[186:187]
	v_pk_fma_f32 v[20:21], v[20:21], v[108:109], v[184:185]
	global_store_dwordx4 v[156:157], v[20:23], off offset:512
	s_waitcnt vmcnt(14)
	v_pk_fma_f32 v[18:19], v[18:19], v[66:67], v[190:191]
	v_pk_fma_f32 v[16:17], v[16:17], v[64:65], v[188:189]
	global_store_dwordx4 v[156:157], v[16:19], off offset:576
	v_lshl_add_u64 v[156:157], v[156:157], 0, s[98:99]
	s_waitcnt vmcnt(13)
	v_pk_fma_f32 v[14:15], v[14:15], v[130:131], v[194:195]
	v_pk_fma_f32 v[12:13], v[12:13], v[128:129], v[192:193]
	global_store_dwordx4 v[156:157], v[12:15], off
	s_waitcnt vmcnt(12)
	v_pk_fma_f32 v[10:11], v[10:11], v[118:119], v[198:199]
	v_pk_fma_f32 v[8:9], v[8:9], v[116:117], v[196:197]
	global_store_dwordx4 v[156:157], v[8:11], off offset:64
	s_waitcnt vmcnt(11)
	v_pk_fma_f32 v[6:7], v[6:7], v[110:111], v[202:203]
	v_pk_fma_f32 v[4:5], v[4:5], v[108:109], v[200:201]
	global_store_dwordx4 v[156:157], v[4:7], off offset:512
	s_waitcnt vmcnt(10)
	v_pk_fma_f32 v[2:3], v[2:3], v[66:67], v[206:207]
	v_pk_fma_f32 v[0:1], v[0:1], v[64:65], v[204:205]
	global_store_dwordx4 v[156:157], v[0:3], off offset:576
	s_andn2_b64 vcc, exec, s[0:1]
	s_cbranch_vccnz .LBB0_1063
	s_andn2_b64 vcc, exec, s[2:3]
	s_cbranch_vccnz .LBB0_1062
	s_branch .LBB0_1062
.LBB0_1077:
	s_waitcnt vmcnt(0)
	s_and_b64 vcc, exec, s[6:7]
	s_cbranch_vccz .Lnoalign_p8
	s_barrier
